# ph_rec: LDS-DMA issue moved to idle helper waves 4-7, o-store acks not waited at step barrier; f3 tile loop de-serialized (all loads in flight)
# speedup vs baseline: 1.0171x; 1.0171x over previous
.LBB0_98:
	v_mov_b64_e32 v[132:133], v[78:79]
	v_mov_b64_e32 v[136:137], v[74:75]
	v_mov_b64_e32 v[140:141], v[70:71]
	v_mov_b64_e32 v[144:145], v[66:67]
	s_cmp_ge_u32 s10, s95
	v_mov_b64_e32 v[130:131], v[76:77]
	v_mov_b64_e32 v[134:135], v[72:73]
	v_mov_b64_e32 v[138:139], v[68:69]
	v_mov_b64_e32 v[142:143], v[64:65]
	v_mov_b32_e32 v128, v172
	s_cbranch_scc1 .LBB0_100
	s_mov_b32 s3, 0x1d51f000
	v_lshl_add_u64 v[80:81], s[80:81], 0, v[170:171]
	v_add_co_u32_e32 v82, vcc, s3, v80
	s_mov_b32 s3, 0x1d521000
	s_nop 0
	v_addc_co_u32_e32 v83, vcc, 0, v81, vcc
	v_add_co_u32_e32 v80, vcc, s3, v80
	s_ashr_i32 s3, s2, 31
	s_lshl_b64 s[8:9], s[2:3], 2
	s_add_u32 s8, s7, s8
	v_readlane_b32 s3, v251, 30
	v_addc_co_u32_e32 v81, vcc, 0, v81, vcc
	s_addc_u32 s9, s3, s9
	global_load_dwordx4 v[130:133], v[82:83], off
	global_load_dwordx4 v[134:137], v[82:83], off offset:1024
	global_load_dwordx4 v[138:141], v[80:81], off
	global_load_dwordx4 v[142:145], v[80:81], off offset:1024
	global_load_dword v128, v129, s[8:9]

.LBB0_101:
	s_waitcnt lgkmcnt(0)
	s_barrier
	s_add_i32 s2, s2, s0
	v_lshl_add_u64 v[166:167], v[166:167], 0, s[50:51]
	v_lshl_add_u64 v[168:169], v[168:169], 0, s[38:39]
	s_cmp_eq_u32 s95, s10
	v_lshl_add_u64 v[170:171], v[170:171], 0, s[38:39]
	s_cbranch_scc1 .LBB0_103
	s_mov_b32 s6, s10
	s_andn2_b64 vcc, exec, s[4:5]
	s_add_i32 s10, s6, 1
	s_cbranch_vccz .LBB0_98
.Lrec_helper:
	s_cmp_ge_u32 s10, s95
	s_cbranch_scc1 .LBB0_101
	s_bitcmp1_b32 s10, 0
	s_cselect_b32 s3, 0xe000, 0
	v_lshl_add_u64 v[80:81], s[80:81], 0, v[168:169]
	s_mov_b64 s[8:9], 0x1d511000
	s_add_i32 s3, s15, s3
	v_lshl_add_u64 v[82:83], v[80:81], 0, s[8:9]
	s_mov_b32 m0, s3
	s_mov_b64 s[8:9], 0x1d511400
	global_load_lds_dwordx4 v[82:83], off
	v_lshl_add_u64 v[82:83], v[80:81], 0, s[8:9]
	s_add_i32 m0, s3, 0x400
	s_mov_b64 s[8:9], 0x1d511800
	global_load_lds_dwordx4 v[82:83], off
	v_lshl_add_u64 v[82:83], v[80:81], 0, s[8:9]
	s_add_i32 m0, s3, 0x800
	s_mov_b64 s[8:9], 0x1d511c00
	global_load_lds_dwordx4 v[82:83], off
	v_lshl_add_u64 v[82:83], v[80:81], 0, s[8:9]
	s_add_i32 m0, s3, 0xc00
	s_mov_b64 s[8:9], 0x1d512000
	global_load_lds_dwordx4 v[82:83], off
	v_lshl_add_u64 v[82:83], v[80:81], 0, s[8:9]
	s_add_i32 m0, s3, 0x1000
	s_mov_b64 s[8:9], 0x1d512400
	global_load_lds_dwordx4 v[82:83], off
	v_lshl_add_u64 v[82:83], v[80:81], 0, s[8:9]
	s_add_i32 m0, s3, 0x1400
	s_mov_b64 s[8:9], 0x1d512800
	global_load_lds_dwordx4 v[82:83], off
	v_lshl_add_u64 v[82:83], v[80:81], 0, s[8:9]
	s_add_i32 m0, s3, 0x1800
	s_mov_b64 s[8:9], 0x1d512c00
	global_load_lds_dwordx4 v[82:83], off
	v_lshl_add_u64 v[82:83], v[80:81], 0, s[8:9]
	s_add_i32 m0, s3, 0x1c00
	s_mov_b64 s[8:9], 0x1d513000
	global_load_lds_dwordx4 v[82:83], off
	v_lshl_add_u64 v[82:83], v[80:81], 0, s[8:9]
	s_add_i32 m0, s3, 0x2000
	s_mov_b64 s[8:9], 0x1d513400
	global_load_lds_dwordx4 v[82:83], off
	v_lshl_add_u64 v[82:83], v[80:81], 0, s[8:9]
	s_add_i32 m0, s3, 0x2400
	s_mov_b64 s[8:9], 0x1d513800
	global_load_lds_dwordx4 v[82:83], off
	v_lshl_add_u64 v[82:83], v[80:81], 0, s[8:9]
	s_add_i32 m0, s3, 0x2800
	s_mov_b64 s[8:9], 0x1d513c00
	global_load_lds_dwordx4 v[82:83], off
	v_lshl_add_u64 v[82:83], v[80:81], 0, s[8:9]
	s_add_i32 m0, s3, 0x2c00
	s_mov_b64 s[8:9], 0x1d514000
	global_load_lds_dwordx4 v[82:83], off
	v_lshl_add_u64 v[82:83], v[80:81], 0, s[8:9]
	s_add_i32 m0, s3, 0x3000
	s_mov_b64 s[8:9], 0x1d514400
	global_load_lds_dwordx4 v[82:83], off
	v_lshl_add_u64 v[80:81], v[80:81], 0, s[8:9]
	s_add_i32 m0, s3, 0x3400
	global_load_lds_dwordx4 v[80:81], off
	s_waitcnt vmcnt(0)
	s_branch .LBB0_101

.LBB0_172:
	s_waitcnt vmcnt(8)
	v_lshl_add_u64 v[92:93], v[90:91], 0, s[2:3]
	v_lshl_add_u64 v[166:167], v[26:27], 0, s[2:3]
	global_load_ushort v130, v[166:167], off
	v_lshl_add_u64 v[168:169], v[28:29], 0, s[2:3]
	global_load_ushort v131, v[168:169], off
	v_lshl_add_u64 v[170:171], v[30:31], 0, s[2:3]
	global_load_ushort v132, v[170:171], off
	v_lshl_add_u64 v[172:173], v[32:33], 0, s[2:3]
	global_load_ushort v133, v[172:173], off
	v_lshl_add_u64 v[166:167], v[34:35], 0, s[2:3]
	global_load_ushort v134, v[166:167], off
	v_lshl_add_u64 v[168:169], v[36:37], 0, s[2:3]
	global_load_ushort v135, v[168:169], off
	v_lshl_add_u64 v[170:171], v[38:39], 0, s[2:3]
	global_load_ushort v136, v[170:171], off
	v_lshl_add_u64 v[172:173], v[40:41], 0, s[2:3]
	global_load_ushort v137, v[172:173], off
	v_lshl_add_u64 v[166:167], v[42:43], 0, s[2:3]
	global_load_ushort v138, v[166:167], off
	v_lshl_add_u64 v[168:169], v[44:45], 0, s[2:3]
	global_load_ushort v139, v[168:169], off
	v_lshl_add_u64 v[170:171], v[46:47], 0, s[2:3]
	global_load_ushort v140, v[170:171], off
	v_lshl_add_u64 v[172:173], v[48:49], 0, s[2:3]
	global_load_ushort v141, v[172:173], off
	v_lshl_add_u64 v[166:167], v[50:51], 0, s[2:3]
	global_load_ushort v142, v[166:167], off
	v_lshl_add_u64 v[168:169], v[52:53], 0, s[2:3]
	global_load_ushort v143, v[168:169], off
	v_lshl_add_u64 v[170:171], v[54:55], 0, s[2:3]
	global_load_ushort v144, v[170:171], off
	v_lshl_add_u64 v[172:173], v[56:57], 0, s[2:3]
	global_load_ushort v145, v[172:173], off
	global_load_dwordx4 v[150:153], v[16:17], off
	global_load_dwordx4 v[154:157], v[18:19], off
	global_load_dwordx4 v[158:161], v[20:21], off
	global_load_dwordx4 v[162:165], v[22:23], off
	s_mov_b64 s[6:7], 0x1c4b8000
	v_lshl_add_u64 v[166:167], v[92:93], 0, s[6:7]
	global_load_ushort v96, v[166:167], off
	s_mov_b64 s[6:7], 0x1c4bc000
	v_lshl_add_u64 v[168:169], v[92:93], 0, s[6:7]
	global_load_ushort v97, v[168:169], off
	s_mov_b64 s[6:7], 0x1c4c0000
	v_lshl_add_u64 v[170:171], v[92:93], 0, s[6:7]
	global_load_ushort v98, v[170:171], off
	s_mov_b64 s[6:7], 0x1c4c4000
	v_lshl_add_u64 v[172:173], v[92:93], 0, s[6:7]
	global_load_ushort v99, v[172:173], off
	s_mov_b64 s[6:7], 0x1c4c8000
	v_lshl_add_u64 v[166:167], v[92:93], 0, s[6:7]
	global_load_ushort v100, v[166:167], off
	s_mov_b64 s[6:7], 0x1c4cc000
	v_lshl_add_u64 v[168:169], v[92:93], 0, s[6:7]
	global_load_ushort v101, v[168:169], off
	s_mov_b64 s[6:7], 0x1c4d0000
	v_lshl_add_u64 v[170:171], v[92:93], 0, s[6:7]
	global_load_ushort v102, v[170:171], off
	s_mov_b64 s[6:7], 0x1c4d4000
	v_lshl_add_u64 v[172:173], v[92:93], 0, s[6:7]
	global_load_ushort v103, v[172:173], off
	s_mov_b64 s[6:7], 0x1c4f8000
	v_lshl_add_u64 v[166:167], v[92:93], 0, s[6:7]
	global_load_ushort v104, v[166:167], off
	s_mov_b64 s[6:7], 0x1c4fc000
	v_lshl_add_u64 v[168:169], v[92:93], 0, s[6:7]
	global_load_ushort v105, v[168:169], off
	s_mov_b64 s[6:7], 0x1c500000
	v_lshl_add_u64 v[170:171], v[92:93], 0, s[6:7]
	global_load_ushort v106, v[170:171], off
	s_mov_b64 s[6:7], 0x1c504000
	v_lshl_add_u64 v[172:173], v[92:93], 0, s[6:7]
	global_load_ushort v107, v[172:173], off
	s_mov_b64 s[6:7], 0x1c508000
	v_lshl_add_u64 v[166:167], v[92:93], 0, s[6:7]
	global_load_ushort v108, v[166:167], off
	s_mov_b64 s[6:7], 0x1c50c000
	v_lshl_add_u64 v[168:169], v[92:93], 0, s[6:7]
	global_load_ushort v109, v[168:169], off
	s_mov_b64 s[6:7], 0x1c510000
	v_lshl_add_u64 v[170:171], v[92:93], 0, s[6:7]
	global_load_ushort v110, v[170:171], off
	s_mov_b64 s[6:7], 0x1c514000
	v_lshl_add_u64 v[172:173], v[92:93], 0, s[6:7]
	global_load_ushort v111, v[172:173], off
	s_mov_b64 s[6:7], 0x1c538000
	v_lshl_add_u64 v[166:167], v[92:93], 0, s[6:7]
	global_load_ushort v112, v[166:167], off
	s_mov_b64 s[6:7], 0x1c53c000
	v_lshl_add_u64 v[168:169], v[92:93], 0, s[6:7]
	global_load_ushort v113, v[168:169], off
	s_mov_b64 s[6:7], 0x1c540000
	v_lshl_add_u64 v[170:171], v[92:93], 0, s[6:7]
	global_load_ushort v114, v[170:171], off
	s_mov_b64 s[6:7], 0x1c544000
	v_lshl_add_u64 v[172:173], v[92:93], 0, s[6:7]
	global_load_ushort v115, v[172:173], off
	s_mov_b64 s[6:7], 0x1c548000
	v_lshl_add_u64 v[166:167], v[92:93], 0, s[6:7]
	global_load_ushort v116, v[166:167], off
	s_mov_b64 s[6:7], 0x1c54c000
	v_lshl_add_u64 v[168:169], v[92:93], 0, s[6:7]
	global_load_ushort v117, v[168:169], off
	s_mov_b64 s[6:7], 0x1c550000
	v_lshl_add_u64 v[170:171], v[92:93], 0, s[6:7]
	global_load_ushort v118, v[170:171], off
	s_mov_b64 s[6:7], 0x1c554000
	v_lshl_add_u64 v[172:173], v[92:93], 0, s[6:7]
	global_load_ushort v119, v[172:173], off
	s_mov_b64 s[6:7], 0x1c578000
	v_lshl_add_u64 v[166:167], v[92:93], 0, s[6:7]
	global_load_ushort v120, v[166:167], off
	s_mov_b64 s[6:7], 0x1c57c000
	v_lshl_add_u64 v[168:169], v[92:93], 0, s[6:7]
	global_load_ushort v121, v[168:169], off
	s_mov_b64 s[6:7], 0x1c580000
	v_lshl_add_u64 v[170:171], v[92:93], 0, s[6:7]
	global_load_ushort v122, v[170:171], off
	s_mov_b64 s[6:7], 0x1c584000
	v_lshl_add_u64 v[172:173], v[92:93], 0, s[6:7]
	global_load_ushort v123, v[172:173], off
	s_mov_b64 s[6:7], 0x1c588000
	v_lshl_add_u64 v[166:167], v[92:93], 0, s[6:7]
	global_load_ushort v124, v[166:167], off
	s_mov_b64 s[6:7], 0x1c58c000
	v_lshl_add_u64 v[168:169], v[92:93], 0, s[6:7]
	global_load_ushort v125, v[168:169], off
	s_mov_b64 s[6:7], 0x1c590000
	v_lshl_add_u64 v[170:171], v[92:93], 0, s[6:7]
	global_load_ushort v126, v[170:171], off
	s_mov_b64 s[6:7], 0x1c594000
	v_lshl_add_u64 v[172:173], v[92:93], 0, s[6:7]
	global_load_ushort v127, v[172:173], off
	s_waitcnt vmcnt(36)
	v_lshlrev_b32_e32 v130, 16, v130
	v_mul_f32_e32 v174, 0xbfb8aa3b, v130
	v_exp_f32_e32 v174, v174
	v_lshlrev_b32_e32 v131, 16, v131
	v_mul_f32_e32 v175, 0xbfb8aa3b, v131
	v_exp_f32_e32 v175, v175
	v_lshlrev_b32_e32 v132, 16, v132
	v_mul_f32_e32 v176, 0xbfb8aa3b, v132
	v_exp_f32_e32 v176, v176
	v_lshlrev_b32_e32 v133, 16, v133
	v_mul_f32_e32 v177, 0xbfb8aa3b, v133
	v_exp_f32_e32 v177, v177
	v_lshlrev_b32_e32 v134, 16, v134
	v_mul_f32_e32 v178, 0xbfb8aa3b, v134
	v_exp_f32_e32 v178, v178
	v_lshlrev_b32_e32 v135, 16, v135
	v_mul_f32_e32 v179, 0xbfb8aa3b, v135
	v_exp_f32_e32 v179, v179
	v_lshlrev_b32_e32 v136, 16, v136
	v_mul_f32_e32 v180, 0xbfb8aa3b, v136
	v_exp_f32_e32 v180, v180
	v_lshlrev_b32_e32 v137, 16, v137
	v_mul_f32_e32 v181, 0xbfb8aa3b, v137
	v_exp_f32_e32 v181, v181
	v_lshlrev_b32_e32 v138, 16, v138
	v_mul_f32_e32 v182, 0xbfb8aa3b, v138
	v_exp_f32_e32 v182, v182
	v_lshlrev_b32_e32 v139, 16, v139
	v_mul_f32_e32 v183, 0xbfb8aa3b, v139
	v_exp_f32_e32 v183, v183
	v_lshlrev_b32_e32 v140, 16, v140
	v_mul_f32_e32 v184, 0xbfb8aa3b, v140
	v_exp_f32_e32 v184, v184
	v_lshlrev_b32_e32 v141, 16, v141
	v_mul_f32_e32 v185, 0xbfb8aa3b, v141
	v_exp_f32_e32 v185, v185
	v_lshlrev_b32_e32 v142, 16, v142
	v_mul_f32_e32 v186, 0xbfb8aa3b, v142
	v_exp_f32_e32 v186, v186
	v_lshlrev_b32_e32 v143, 16, v143
	v_mul_f32_e32 v187, 0xbfb8aa3b, v143
	v_exp_f32_e32 v187, v187
	v_lshlrev_b32_e32 v144, 16, v144
	v_mul_f32_e32 v188, 0xbfb8aa3b, v144
	v_exp_f32_e32 v188, v188
	v_lshlrev_b32_e32 v145, 16, v145
	v_mul_f32_e32 v189, 0xbfb8aa3b, v145
	v_exp_f32_e32 v189, v189
	s_nop 0
	v_add_f32_e32 v174, 1.0, v174
	v_add_f32_e32 v175, 1.0, v175
	v_add_f32_e32 v176, 1.0, v176
	v_add_f32_e32 v177, 1.0, v177
	v_add_f32_e32 v178, 1.0, v178
	v_add_f32_e32 v179, 1.0, v179
	v_add_f32_e32 v180, 1.0, v180
	v_add_f32_e32 v181, 1.0, v181
	v_add_f32_e32 v182, 1.0, v182
	v_add_f32_e32 v183, 1.0, v183
	v_add_f32_e32 v184, 1.0, v184
	v_add_f32_e32 v185, 1.0, v185
	v_add_f32_e32 v186, 1.0, v186
	v_add_f32_e32 v187, 1.0, v187
	v_add_f32_e32 v188, 1.0, v188
	v_add_f32_e32 v189, 1.0, v189
	v_rcp_f32_e32 v174, v174
	v_rcp_f32_e32 v175, v175
	v_rcp_f32_e32 v176, v176
	v_rcp_f32_e32 v177, v177
	v_rcp_f32_e32 v178, v178
	v_rcp_f32_e32 v179, v179
	v_rcp_f32_e32 v180, v180
	v_rcp_f32_e32 v181, v181
	v_rcp_f32_e32 v182, v182
	v_rcp_f32_e32 v183, v183
	v_rcp_f32_e32 v184, v184
	v_rcp_f32_e32 v185, v185
	v_rcp_f32_e32 v186, v186
	v_rcp_f32_e32 v187, v187
	v_rcp_f32_e32 v188, v188
	v_rcp_f32_e32 v189, v189
	s_nop 0
	v_mul_f32_e32 v130, v174, v130
	v_mul_f32_e32 v131, v175, v131
	v_mul_f32_e32 v132, v176, v132
	v_mul_f32_e32 v133, v177, v133
	v_mul_f32_e32 v134, v178, v134
	v_mul_f32_e32 v135, v179, v135
	v_mul_f32_e32 v136, v180, v136
	v_mul_f32_e32 v137, v181, v137
	v_mul_f32_e32 v138, v182, v138
	v_mul_f32_e32 v139, v183, v139
	v_mul_f32_e32 v140, v184, v140
	v_mul_f32_e32 v141, v185, v141
	v_mul_f32_e32 v142, v186, v142
	v_mul_f32_e32 v143, v187, v143
	v_mul_f32_e32 v144, v188, v144
	v_mul_f32_e32 v145, v189, v145
	s_waitcnt vmcnt(0)
	v_lshl_or_b32 v190, v97, 16, v96
	v_lshl_or_b32 v191, v99, 16, v98
	v_lshl_or_b32 v192, v101, 16, v100
	v_lshl_or_b32 v193, v103, 16, v102
	v_lshl_or_b32 v194, v105, 16, v104
	v_lshl_or_b32 v195, v107, 16, v106
	v_lshl_or_b32 v196, v109, 16, v108
	v_lshl_or_b32 v197, v111, 16, v110
	v_lshl_or_b32 v198, v113, 16, v112
	v_lshl_or_b32 v199, v115, 16, v114
	v_lshl_or_b32 v200, v117, 16, v116
	v_lshl_or_b32 v201, v119, 16, v118
	v_lshl_or_b32 v202, v121, 16, v120
	v_lshl_or_b32 v203, v123, 16, v122
	v_lshl_or_b32 v204, v125, 16, v124
	v_lshl_or_b32 v205, v127, 16, v126
	s_nop 1
	v_mfma_f32_32x32x16_bf16 v[0:15], v[150:153], v[190:193], 0
	v_mfma_f32_32x32x16_bf16 v[0:15], v[154:157], v[194:197], v[0:15]
	v_mfma_f32_32x32x16_bf16 v[0:15], v[158:161], v[198:201], v[0:15]
	v_mfma_f32_32x32x16_bf16 v[0:15], v[162:165], v[202:205], v[0:15]
	v_lshl_add_u64 v[96:97], v[58:59], 0, s[2:3]
	v_lshl_add_u64 v[98:99], v[60:61], 0, s[2:3]
	v_lshl_add_u64 v[100:101], v[62:63], 0, s[2:3]
	v_lshl_add_u64 v[102:103], v[64:65], 0, s[2:3]
	v_lshl_add_u64 v[104:105], v[66:67], 0, s[2:3]
	v_lshl_add_u64 v[106:107], v[68:69], 0, s[2:3]
	v_lshl_add_u64 v[108:109], v[70:71], 0, s[2:3]
	v_lshl_add_u64 v[110:111], v[72:73], 0, s[2:3]
	v_lshl_add_u64 v[112:113], v[74:75], 0, s[2:3]
	v_lshl_add_u64 v[114:115], v[76:77], 0, s[2:3]
	v_lshl_add_u64 v[116:117], v[78:79], 0, s[2:3]
	v_lshl_add_u64 v[118:119], v[80:81], 0, s[2:3]
	v_lshl_add_u64 v[120:121], v[82:83], 0, s[2:3]
	v_lshl_add_u64 v[122:123], v[84:85], 0, s[2:3]
	v_lshl_add_u64 v[124:125], v[86:87], 0, s[2:3]
	v_lshl_add_u64 v[126:127], v[88:89], 0, s[2:3]
	v_mul_f32_e32 v0, 0x3b000000, v0
	v_mul_f32_e32 v1, 0x3b000000, v1
	v_mul_f32_e32 v2, 0x3b000000, v2
	v_mul_f32_e32 v3, 0x3b000000, v3
	v_mul_f32_e32 v4, 0x3b000000, v4
	v_mul_f32_e32 v5, 0x3b000000, v5
	v_mul_f32_e32 v6, 0x3b000000, v6
	v_mul_f32_e32 v7, 0x3b000000, v7
	v_mul_f32_e32 v8, 0x3b000000, v8
	v_mul_f32_e32 v9, 0x3b000000, v9
	v_mul_f32_e32 v10, 0x3b000000, v10
	v_mul_f32_e32 v11, 0x3b000000, v11
	v_mul_f32_e32 v12, 0x3b000000, v12
	v_mul_f32_e32 v13, 0x3b000000, v13
	v_mul_f32_e32 v14, 0x3b000000, v14
	v_mul_f32_e32 v15, 0x3b000000, v15
	v_mul_f32_e32 v0, v0, v130
	v_mul_f32_e32 v1, v1, v131
	v_mul_f32_e32 v2, v2, v132
	v_mul_f32_e32 v3, v3, v133
	v_mul_f32_e32 v4, v4, v134
	v_mul_f32_e32 v5, v5, v135
	v_mul_f32_e32 v6, v6, v136
	v_mul_f32_e32 v7, v7, v137
	v_mul_f32_e32 v8, v8, v138
	v_mul_f32_e32 v9, v9, v139
	v_mul_f32_e32 v10, v10, v140
	v_mul_f32_e32 v11, v11, v141
	v_mul_f32_e32 v12, v12, v142
	v_mul_f32_e32 v13, v13, v143
	v_mul_f32_e32 v14, v14, v144
	v_mul_f32_e32 v15, v15, v145
	v_cvt_pk_bf16_f32 v0, v0, s0
	v_cvt_pk_bf16_f32 v1, v1, s0
	v_cvt_pk_bf16_f32 v2, v2, s0
	v_cvt_pk_bf16_f32 v3, v3, s0
	v_cvt_pk_bf16_f32 v4, v4, s0
	v_cvt_pk_bf16_f32 v5, v5, s0
	v_cvt_pk_bf16_f32 v6, v6, s0
	v_cvt_pk_bf16_f32 v7, v7, s0
	v_cvt_pk_bf16_f32 v8, v8, s0
	v_cvt_pk_bf16_f32 v9, v9, s0
	v_cvt_pk_bf16_f32 v10, v10, s0
	v_cvt_pk_bf16_f32 v11, v11, s0
	v_cvt_pk_bf16_f32 v12, v12, s0
	v_cvt_pk_bf16_f32 v13, v13, s0
	v_cvt_pk_bf16_f32 v14, v14, s0
	v_cvt_pk_bf16_f32 v15, v15, s0
	global_store_short v[96:97], v0, off
	global_store_short v[98:99], v1, off
	global_store_short v[100:101], v2, off
	global_store_short v[102:103], v3, off
	global_store_short v[104:105], v4, off
	global_store_short v[106:107], v5, off
	global_store_short v[108:109], v6, off
	global_store_short v[110:111], v7, off
	global_store_short v[112:113], v8, off
	global_store_short v[114:115], v9, off
	global_store_short v[116:117], v10, off
	global_store_short v[118:119], v11, off
	global_store_short v[120:121], v12, off
	global_store_short v[122:123], v13, off
	global_store_short v[124:125], v14, off
	global_store_short v[126:127], v15, off
	s_add_u32 s2, s2, 64
	s_addc_u32 s3, s3, 0
	s_cmpk_lg_i32 s2, 0x100
	s_cbranch_scc1 .LBB0_172
	v_readlane_b32 s0, v251, 44
	s_add_i32 s1, s0, s1
	v_readlane_b32 s0, v254, 9
	v_readlane_b32 s2, v254, 60
	s_add_i32 s4, s4, s0
	s_add_i32 s5, s5, s2
	s_cmpk_gt_i32 s1, 0x3ff
	v_readlane_b32 s3, v254, 61
	s_cbranch_scc0 .LBB0_171

.LBB0_191:
	s_mul_hi_i32 s0, s28, 0x2aaaaaab
	s_lshr_b32 s1, s0, 31
	s_ashr_i32 s0, s0, 1
	s_add_i32 s1, s0, s1
	v_mbcnt_lo_u32_b32 v216, -1, 0
	v_mbcnt_hi_u32_b32 v216, -1, v216
	s_mul_i32 s0, s1, -12
	v_and_b32_e32 v128, 7, v216
	s_add_i32 s2, s0, s28
	v_lshlrev_b32_e32 v215, 4, v128
	v_lshl_or_b32 v48, s2, 7, v215
	v_add_u32_e32 v0, 0x600, v48
	v_add_u32_e32 v48, 0xc00, v48
	v_ashrrev_i32_e32 v1, 31, v0
	v_ashrrev_i32_e32 v49, 31, v48
	v_lshlrev_b64 v[0:1], 2, v[0:1]
	v_lshlrev_b64 v[48:49], 2, v[48:49]
	v_lshl_add_u64 v[4:5], s[34:35], 0, v[0:1]
	v_lshl_add_u64 v[6:7], s[56:57], 0, v[0:1]
	v_lshl_add_u64 v[40:41], s[50:51], 0, v[0:1]
	v_lshl_add_u64 v[52:53], s[34:35], 0, v[48:49]
	v_lshl_add_u64 v[56:57], s[56:57], 0, v[48:49]
	global_load_dwordx4 v[0:3], v[4:5], off
	global_load_dwordx4 v[12:15], v[4:5], off offset:16
	global_load_dwordx4 v[24:27], v[4:5], off offset:32
	global_load_dwordx4 v[36:39], v[4:5], off offset:48
	global_load_dwordx4 v[8:11], v[6:7], off
	global_load_dwordx4 v[20:23], v[6:7], off offset:16
	global_load_dwordx4 v[32:35], v[6:7], off offset:32
	global_load_dwordx4 v[44:47], v[6:7], off offset:48
	s_nop 0
	global_load_dwordx4 v[4:7], v[40:41], off
	global_load_dwordx4 v[16:19], v[40:41], off offset:16
	global_load_dwordx4 v[28:31], v[40:41], off offset:32
	s_nop 0
	global_load_dwordx4 v[40:43], v[40:41], off offset:48
	v_lshl_add_u64 v[210:211], s[50:51], 0, v[48:49]
	global_load_dwordx4 v[48:51], v[52:53], off offset:48
	global_load_dwordx4 v[60:63], v[52:53], off offset:32
	global_load_dwordx4 v[194:197], v[52:53], off offset:16
	global_load_dwordx4 v[206:209], v[52:53], off
	s_nop 0
	global_load_dwordx4 v[52:55], v[56:57], off offset:48
	global_load_dwordx4 v[186:189], v[56:57], off offset:32
	global_load_dwordx4 v[198:201], v[56:57], off offset:16
	global_load_dwordx4 v[218:221], v[56:57], off
	s_nop 0
	global_load_dwordx4 v[56:59], v[210:211], off offset:48
	global_load_dwordx4 v[190:193], v[210:211], off offset:32
	global_load_dwordx4 v[202:205], v[210:211], off offset:16
	global_load_dwordx4 v[222:225], v[210:211], off
	s_waitcnt vmcnt(0)
	v_lshlrev_b32_e32 v212, 16, v178
	v_and_b32_e32 v213, 0xffff0000, v178
	v_lshlrev_b32_e32 v210, 16, v182
	v_and_b32_e32 v211, 0xffff0000, v182
	v_lshlrev_b32_e32 v178, 16, v179
	v_and_b32_e32 v179, 0xffff0000, v179
	v_lshlrev_b32_e32 v182, 16, v183
	v_and_b32_e32 v183, 0xffff0000, v183
	v_and_b32_e32 v214, 63, v216
	s_mov_b32 s0, 0x358637bd
	v_pk_mul_f32 v[212:213], v[218:219], v[212:213]
	s_nop 0
	v_pk_fma_f32 v[206:207], v[206:207], v[210:211], v[212:213]
	v_lshlrev_b32_e32 v210, 16, v174
	v_and_b32_e32 v211, 0xffff0000, v174
	v_pk_fma_f32 v[206:207], v[222:223], v[210:211], v[206:207]
	v_pk_mul_f32 v[178:179], v[220:221], v[178:179]
	v_mul_f32_e32 v174, 0xbfb8aa3b, v206
	v_exp_f32_e32 v174, v174
	v_pk_fma_f32 v[178:179], v[208:209], v[182:183], v[178:179]
	v_lshlrev_b32_e32 v182, 16, v180
	v_and_b32_e32 v183, 0xffff0000, v180
	v_add_f32_e32 v174, 1.0, v174
	v_rcp_f32_e32 v210, v174
	v_mul_f32_e32 v174, 0xbfb8aa3b, v207
	v_exp_f32_e32 v174, v174
	v_pk_mul_f32 v[182:183], v[198:199], v[182:183]
	v_lshlrev_b32_e32 v180, 16, v181
	v_and_b32_e32 v181, 0xffff0000, v181
	v_add_f32_e32 v174, 1.0, v174
	v_rcp_f32_e32 v211, v174
	v_lshlrev_b32_e32 v174, 16, v175
	v_and_b32_e32 v175, 0xffff0000, v175
	v_pk_fma_f32 v[174:175], v[224:225], v[174:175], v[178:179]
	v_pk_mul_f32 v[180:181], v[200:201], v[180:181]
	v_mul_f32_e32 v178, 0xbfb8aa3b, v174
	v_mul_f32_e32 v179, 0xbfb8aa3b, v175
	v_exp_f32_e32 v178, v178
	v_exp_f32_e32 v179, v179
	v_pk_mul_f32 v[212:213], v[206:207], v[210:211]
	v_add_f32_e32 v178, 1.0, v178
	v_add_f32_e32 v179, 1.0, v179
	v_rcp_f32_e32 v178, v178
	v_rcp_f32_e32 v179, v179
	s_nop 0
	v_pk_mul_f32 v[174:175], v[174:175], v[178:179]
	v_lshlrev_b32_e32 v178, 16, v184
	v_and_b32_e32 v179, 0xffff0000, v184
	v_pk_fma_f32 v[178:179], v[194:195], v[178:179], v[182:183]
	v_lshlrev_b32_e32 v182, 16, v176
	v_and_b32_e32 v183, 0xffff0000, v176
	v_pk_fma_f32 v[178:179], v[202:203], v[182:183], v[178:179]
	s_nop 0
	v_mul_f32_e32 v176, 0xbfb8aa3b, v178
	v_exp_f32_e32 v176, v176
	s_nop 0
	v_add_f32_e32 v176, 1.0, v176
	v_rcp_f32_e32 v182, v176
	v_mul_f32_e32 v176, 0xbfb8aa3b, v179
	v_exp_f32_e32 v176, v176
	s_nop 0
	v_add_f32_e32 v176, 1.0, v176
	v_rcp_f32_e32 v183, v176
	v_lshlrev_b32_e32 v176, 16, v177
	v_and_b32_e32 v177, 0xffff0000, v177
	v_pk_mul_f32 v[178:179], v[178:179], v[182:183]
	v_lshlrev_b32_e32 v182, 16, v185
	v_and_b32_e32 v183, 0xffff0000, v185
	v_pk_fma_f32 v[180:181], v[196:197], v[182:183], v[180:181]
	v_lshlrev_b32_e32 v182, 16, v124
	v_pk_fma_f32 v[176:177], v[204:205], v[176:177], v[180:181]
	v_and_b32_e32 v183, 0xffff0000, v124
	v_mul_f32_e32 v180, 0xbfb8aa3b, v176
	v_mul_f32_e32 v181, 0xbfb8aa3b, v177
	v_exp_f32_e32 v180, v180
	v_exp_f32_e32 v181, v181
	v_pk_mul_f32 v[182:183], v[186:187], v[182:183]
	v_add_u32_e32 v186, s87, v216
	v_add_f32_e32 v180, 1.0, v180
	v_add_f32_e32 v181, 1.0, v181
	v_rcp_f32_e32 v180, v180
	v_rcp_f32_e32 v181, v181
	v_ashrrev_i32_e32 v187, 3, v186
	v_pk_mul_f32 v[176:177], v[176:177], v[180:181]
	v_lshlrev_b32_e32 v180, 16, v134
	v_and_b32_e32 v181, 0xffff0000, v134
	v_pk_fma_f32 v[60:61], v[60:61], v[180:181], v[182:183]
	v_lshlrev_b32_e32 v180, 16, v146
	v_and_b32_e32 v181, 0xffff0000, v146
	v_pk_fma_f32 v[60:61], v[190:191], v[180:181], v[60:61]
	v_lshlrev_b32_e32 v134, 16, v135
	v_mul_f32_e32 v124, 0xbfb8aa3b, v60
	v_exp_f32_e32 v124, v124
	v_and_b32_e32 v135, 0xffff0000, v135
	v_add_f32_e32 v124, 1.0, v124
	v_rcp_f32_e32 v180, v124
	v_mul_f32_e32 v124, 0xbfb8aa3b, v61
	v_exp_f32_e32 v124, v124
	s_nop 0
	v_add_f32_e32 v124, 1.0, v124
	v_rcp_f32_e32 v181, v124
	v_lshlrev_b32_e32 v124, 16, v125
	v_and_b32_e32 v125, 0xffff0000, v125
	v_pk_mul_f32 v[124:125], v[188:189], v[124:125]
	v_pk_mul_f32 v[60:61], v[60:61], v[180:181]
	v_pk_fma_f32 v[62:63], v[62:63], v[134:135], v[124:125]
	v_lshlrev_b32_e32 v124, 16, v147
	v_and_b32_e32 v125, 0xffff0000, v147
	v_pk_fma_f32 v[62:63], v[192:193], v[124:125], v[62:63]
	v_lshlrev_b32_e32 v134, 16, v126
	v_mul_f32_e32 v124, 0xbfb8aa3b, v62
	v_mul_f32_e32 v125, 0xbfb8aa3b, v63
	v_exp_f32_e32 v124, v124
	v_exp_f32_e32 v125, v125
	v_and_b32_e32 v135, 0xffff0000, v126
	v_pk_mul_f32 v[52:53], v[52:53], v[134:135]
	v_add_f32_e32 v124, 1.0, v124
	v_add_f32_e32 v125, 1.0, v125
	v_rcp_f32_e32 v124, v124
	v_rcp_f32_e32 v125, v125
	s_nop 0
	v_pk_mul_f32 v[62:63], v[62:63], v[124:125]
	v_lshlrev_b32_e32 v124, 16, v136
	v_and_b32_e32 v125, 0xffff0000, v136
	v_pk_fma_f32 v[48:49], v[48:49], v[124:125], v[52:53]
	v_lshlrev_b32_e32 v52, 16, v148
	v_and_b32_e32 v53, 0xffff0000, v148
	v_pk_fma_f32 v[48:49], v[56:57], v[52:53], v[48:49]
	v_lshlrev_b32_e32 v56, 16, v127
	v_mul_f32_e32 v52, 0xbfb8aa3b, v48
	v_mul_f32_e32 v53, 0xbfb8aa3b, v49
	v_exp_f32_e32 v52, v52
	v_exp_f32_e32 v53, v53
	v_and_b32_e32 v57, 0xffff0000, v127
	v_pk_mul_f32 v[54:55], v[54:55], v[56:57]
	v_add_f32_e32 v52, 1.0, v52
	v_add_f32_e32 v53, 1.0, v53
	v_rcp_f32_e32 v52, v52
	v_rcp_f32_e32 v53, v53
	v_lshlrev_b32_e32 v124, 2, v214
	v_xor_b32_e32 v127, 4, v124
	v_xor_b32_e32 v126, 8, v124
	v_pk_mul_f32 v[48:49], v[48:49], v[52:53]
	v_lshlrev_b32_e32 v52, 16, v137
	v_and_b32_e32 v53, 0xffff0000, v137
	v_pk_fma_f32 v[50:51], v[50:51], v[52:53], v[54:55]
	v_lshlrev_b32_e32 v52, 16, v149
	v_and_b32_e32 v53, 0xffff0000, v149
	v_pk_fma_f32 v[50:51], v[58:59], v[52:53], v[50:51]
	v_lshlrev_b32_e32 v54, 16, v99
	v_mul_f32_e32 v52, 0xbfb8aa3b, v50
	v_mul_f32_e32 v53, 0xbfb8aa3b, v51
	v_exp_f32_e32 v52, v52
	v_exp_f32_e32 v53, v53
	v_and_b32_e32 v55, 0xffff0000, v99
	v_pk_mul_f32 v[54:55], v[168:169], v[54:55]
	v_add_f32_e32 v52, 1.0, v52
	v_add_f32_e32 v53, 1.0, v53
	v_rcp_f32_e32 v52, v52
	v_rcp_f32_e32 v53, v53
	v_lshlrev_b32_e32 v58, 16, v98
	v_and_b32_e32 v59, 0xffff0000, v98
	v_pk_mul_f32 v[58:59], v[166:167], v[58:59]
	v_pk_mul_f32 v[50:51], v[50:51], v[52:53]
	v_lshlrev_b32_e32 v52, 16, v107
	v_and_b32_e32 v53, 0xffff0000, v107
	v_pk_fma_f32 v[52:53], v[164:165], v[52:53], v[54:55]
	v_lshlrev_b32_e32 v54, 16, v111
	v_and_b32_e32 v55, 0xffff0000, v111
	v_pk_fma_f32 v[52:53], v[172:173], v[54:55], v[52:53]
	v_and_b32_e32 v107, 0xffff0000, v97
	v_mul_f32_e32 v54, 0xbfb8aa3b, v52
	v_mul_f32_e32 v55, 0xbfb8aa3b, v53
	v_exp_f32_e32 v54, v54
	v_exp_f32_e32 v55, v55
	v_and_b32_e32 v111, 0xffff0000, v104
	v_xor_b32_e32 v125, 16, v124
	v_add_f32_e32 v54, 1.0, v54
	v_add_f32_e32 v55, 1.0, v55
	v_rcp_f32_e32 v54, v54
	v_rcp_f32_e32 v55, v55
	s_nop 0
	v_pk_mul_f32 v[52:53], v[52:53], v[54:55]
	v_lshlrev_b32_e32 v54, 16, v106
	v_and_b32_e32 v55, 0xffff0000, v106
	v_pk_fma_f32 v[54:55], v[162:163], v[54:55], v[58:59]
	v_lshlrev_b32_e32 v58, 16, v110
	v_and_b32_e32 v59, 0xffff0000, v110
	v_pk_fma_f32 v[54:55], v[170:171], v[58:59], v[54:55]
	v_lshlrev_b32_e32 v106, 16, v97
	v_mul_f32_e32 v58, 0xbfb8aa3b, v54
	v_mul_f32_e32 v59, 0xbfb8aa3b, v55
	v_exp_f32_e32 v58, v58
	v_exp_f32_e32 v59, v59
	v_pk_mul_f32 v[106:107], v[156:157], v[106:107]
	v_lshlrev_b32_e32 v110, 16, v104
	v_add_f32_e32 v58, 1.0, v58
	v_add_f32_e32 v59, 1.0, v59
	v_rcp_f32_e32 v58, v58
	v_rcp_f32_e32 v59, v59
	v_lshlrev_b32_e32 v104, 16, v96
	v_pk_mul_f32 v[56:57], v[52:53], v[52:53]
	v_pk_mul_f32 v[54:55], v[54:55], v[58:59]
	v_lshlrev_b32_e32 v58, 16, v105
	v_and_b32_e32 v59, 0xffff0000, v105
	v_pk_fma_f32 v[58:59], v[152:153], v[58:59], v[106:107]
	v_lshlrev_b32_e32 v106, 16, v109
	v_and_b32_e32 v107, 0xffff0000, v109
	v_pk_fma_f32 v[58:59], v[160:161], v[106:107], v[58:59]
	v_and_b32_e32 v105, 0xffff0000, v96
	v_mul_f32_e32 v97, 0xbfb8aa3b, v58
	v_exp_f32_e32 v97, v97
	v_pk_mul_f32 v[98:99], v[54:55], v[54:55]
	v_add_f32_e32 v97, 1.0, v97
	v_rcp_f32_e32 v106, v97
	v_mul_f32_e32 v97, 0xbfb8aa3b, v59
	v_exp_f32_e32 v97, v97
	s_nop 0
	v_add_f32_e32 v97, 1.0, v97
	v_rcp_f32_e32 v107, v97
	v_pk_mul_f32 v[96:97], v[154:155], v[104:105]
	v_lshlrev_b32_e32 v104, 16, v108
	v_pk_fma_f32 v[96:97], v[150:151], v[110:111], v[96:97]
	v_and_b32_e32 v105, 0xffff0000, v108
	v_pk_fma_f32 v[96:97], v[158:159], v[104:105], v[96:97]
	v_lshlrev_b32_e32 v110, 16, v75
	v_mul_f32_e32 v104, 0xbfb8aa3b, v96
	v_mul_f32_e32 v105, 0xbfb8aa3b, v97
	v_exp_f32_e32 v104, v104
	v_exp_f32_e32 v105, v105
	v_and_b32_e32 v111, 0xffff0000, v75
	v_pk_mul_f32 v[110:111], v[140:141], v[110:111]
	v_add_f32_e32 v104, 1.0, v104
	v_add_f32_e32 v105, 1.0, v105
	v_rcp_f32_e32 v104, v104
	v_rcp_f32_e32 v105, v105
	v_pk_mul_f32 v[58:59], v[58:59], v[106:107]
	v_pk_mul_f32 v[96:97], v[96:97], v[104:105]
	v_lshlrev_b32_e32 v104, 16, v91
	v_and_b32_e32 v105, 0xffff0000, v91
	v_pk_fma_f32 v[104:105], v[132:133], v[104:105], v[110:111]
	v_lshlrev_b32_e32 v110, 16, v87
	v_and_b32_e32 v111, 0xffff0000, v87
	v_pk_fma_f32 v[104:105], v[144:145], v[110:111], v[104:105]
	v_and_b32_e32 v91, 0xffff0000, v74
	v_mul_f32_e32 v75, 0xbfb8aa3b, v104
	v_exp_f32_e32 v75, v75
	v_pk_mul_f32 v[108:109], v[96:97], v[96:97]
	v_pk_mul_f32 v[106:107], v[58:59], v[58:59]
	v_add_f32_e32 v75, 1.0, v75
	v_rcp_f32_e32 v110, v75
	v_mul_f32_e32 v75, 0xbfb8aa3b, v105
	v_exp_f32_e32 v75, v75
	s_nop 0
	v_add_f32_e32 v75, 1.0, v75
	v_rcp_f32_e32 v111, v75
	s_nop 0
	v_pk_mul_f32 v[104:105], v[104:105], v[110:111]
	v_lshlrev_b32_e32 v110, 16, v90
	v_and_b32_e32 v111, 0xffff0000, v90
	v_lshlrev_b32_e32 v90, 16, v74
	v_pk_mul_f32 v[74:75], v[138:139], v[90:91]
	v_lshlrev_b32_e32 v90, 16, v86
	v_pk_fma_f32 v[74:75], v[130:131], v[110:111], v[74:75]
	v_and_b32_e32 v91, 0xffff0000, v86
	v_pk_fma_f32 v[74:75], v[142:143], v[90:91], v[74:75]
	v_lshlrev_b32_e32 v90, 16, v73
	v_mul_f32_e32 v86, 0xbfb8aa3b, v74
	v_mul_f32_e32 v87, 0xbfb8aa3b, v75
	v_exp_f32_e32 v86, v86
	v_exp_f32_e32 v87, v87
	v_and_b32_e32 v91, 0xffff0000, v73
	v_pk_mul_f32 v[90:91], v[118:119], v[90:91]
	v_add_f32_e32 v86, 1.0, v86
	v_add_f32_e32 v87, 1.0, v87
	v_rcp_f32_e32 v86, v86
	v_rcp_f32_e32 v87, v87
	s_nop 0
	v_pk_mul_f32 v[74:75], v[74:75], v[86:87]
	v_lshlrev_b32_e32 v86, 16, v89
	v_and_b32_e32 v87, 0xffff0000, v89
	v_pk_fma_f32 v[86:87], v[114:115], v[86:87], v[90:91]
	v_lshlrev_b32_e32 v90, 16, v85
	v_and_b32_e32 v91, 0xffff0000, v85
	v_pk_fma_f32 v[86:87], v[122:123], v[90:91], v[86:87]
	v_and_b32_e32 v89, 0xffff0000, v72
	v_mul_f32_e32 v73, 0xbfb8aa3b, v86
	v_exp_f32_e32 v73, v73
	s_nop 0
	v_add_f32_e32 v73, 1.0, v73
	v_rcp_f32_e32 v90, v73
	v_mul_f32_e32 v73, 0xbfb8aa3b, v87
	v_exp_f32_e32 v73, v73
	s_nop 0
	v_add_f32_e32 v73, 1.0, v73
	v_rcp_f32_e32 v91, v73
	s_nop 0
	v_pk_mul_f32 v[86:87], v[86:87], v[90:91]
	v_lshlrev_b32_e32 v90, 16, v88
	v_and_b32_e32 v91, 0xffff0000, v88
	v_lshlrev_b32_e32 v88, 16, v72
	v_pk_mul_f32 v[72:73], v[116:117], v[88:89]
	v_lshlrev_b32_e32 v88, 16, v84
	v_pk_fma_f32 v[72:73], v[112:113], v[90:91], v[72:73]
	v_and_b32_e32 v89, 0xffff0000, v84
	v_pk_fma_f32 v[72:73], v[120:121], v[88:89], v[72:73]
	v_lshlrev_b32_e32 v88, 16, v83
	v_mul_f32_e32 v84, 0xbfb8aa3b, v72
	v_mul_f32_e32 v85, 0xbfb8aa3b, v73
	v_exp_f32_e32 v84, v84
	v_exp_f32_e32 v85, v85
	v_and_b32_e32 v89, 0xffff0000, v83
	v_pk_mul_f32 v[46:47], v[46:47], v[88:89]
	v_add_f32_e32 v84, 1.0, v84
	v_add_f32_e32 v85, 1.0, v85
	v_rcp_f32_e32 v84, v84
	v_rcp_f32_e32 v85, v85
	s_nop 0
	v_pk_mul_f32 v[72:73], v[72:73], v[84:85]
	v_lshlrev_b32_e32 v84, 16, v95
	v_and_b32_e32 v85, 0xffff0000, v95
	v_pk_fma_f32 v[38:39], v[38:39], v[84:85], v[46:47]
	v_lshlrev_b32_e32 v46, 16, v103
	v_and_b32_e32 v47, 0xffff0000, v103
	v_lshlrev_b32_e32 v84, 16, v82
	v_and_b32_e32 v85, 0xffff0000, v82
	v_pk_fma_f32 v[38:39], v[42:43], v[46:47], v[38:39]
	v_lshlrev_b32_e32 v46, 16, v94
	v_and_b32_e32 v47, 0xffff0000, v94
	v_pk_mul_f32 v[44:45], v[44:45], v[84:85]
	v_mul_f32_e32 v42, 0xbfb8aa3b, v38
	v_pk_fma_f32 v[36:37], v[36:37], v[46:47], v[44:45]
	v_lshlrev_b32_e32 v44, 16, v102
	v_and_b32_e32 v45, 0xffff0000, v102
	v_lshlrev_b32_e32 v46, 16, v81
	v_and_b32_e32 v47, 0xffff0000, v81
	v_pk_fma_f32 v[36:37], v[40:41], v[44:45], v[36:37]
	v_lshlrev_b32_e32 v44, 16, v93
	v_and_b32_e32 v45, 0xffff0000, v93
	v_pk_mul_f32 v[34:35], v[34:35], v[46:47]
	v_mul_f32_e32 v40, 0xbfb8aa3b, v36
	v_pk_fma_f32 v[26:27], v[26:27], v[44:45], v[34:35]
	v_lshlrev_b32_e32 v34, 16, v101
	v_and_b32_e32 v35, 0xffff0000, v101
	v_lshlrev_b32_e32 v44, 16, v80
	v_and_b32_e32 v45, 0xffff0000, v80
	v_pk_fma_f32 v[26:27], v[30:31], v[34:35], v[26:27]
	v_lshlrev_b32_e32 v34, 16, v92
	v_and_b32_e32 v35, 0xffff0000, v92
	v_pk_mul_f32 v[32:33], v[32:33], v[44:45]
	v_mul_f32_e32 v30, 0xbfb8aa3b, v26
	v_pk_fma_f32 v[24:25], v[24:25], v[34:35], v[32:33]
	v_lshlrev_b32_e32 v32, 16, v100
	v_and_b32_e32 v33, 0xffff0000, v100
	v_lshlrev_b32_e32 v34, 16, v67
	v_and_b32_e32 v35, 0xffff0000, v67
	v_pk_fma_f32 v[24:25], v[28:29], v[32:33], v[24:25]
	v_lshlrev_b32_e32 v32, 16, v71
	v_and_b32_e32 v33, 0xffff0000, v71
	v_pk_mul_f32 v[22:23], v[22:23], v[34:35]
	v_mul_f32_e32 v28, 0xbfb8aa3b, v24
	v_pk_fma_f32 v[14:15], v[14:15], v[32:33], v[22:23]
	v_lshlrev_b32_e32 v22, 16, v79
	v_and_b32_e32 v23, 0xffff0000, v79
	v_pk_fma_f32 v[14:15], v[18:19], v[22:23], v[14:15]
	v_lshlrev_b32_e32 v22, 16, v66
	v_mul_f32_e32 v18, 0xbfb8aa3b, v14
	v_mul_f32_e32 v19, 0xbfb8aa3b, v15
	v_exp_f32_e32 v18, v18
	v_exp_f32_e32 v19, v19
	v_and_b32_e32 v23, 0xffff0000, v66
	v_pk_mul_f32 v[20:21], v[20:21], v[22:23]
	v_add_f32_e32 v18, 1.0, v18
	v_add_f32_e32 v19, 1.0, v19
	v_rcp_f32_e32 v18, v18
	v_rcp_f32_e32 v19, v19
	v_mul_f32_e32 v29, 0xbfb8aa3b, v25
	v_exp_f32_e32 v28, v28
	v_exp_f32_e32 v29, v29
	v_pk_mul_f32 v[14:15], v[14:15], v[18:19]
	v_lshlrev_b32_e32 v18, 16, v70
	v_and_b32_e32 v19, 0xffff0000, v70
	v_pk_fma_f32 v[12:13], v[12:13], v[18:19], v[20:21]
	v_lshlrev_b32_e32 v18, 16, v78
	v_and_b32_e32 v19, 0xffff0000, v78
	v_pk_fma_f32 v[12:13], v[16:17], v[18:19], v[12:13]
	v_lshlrev_b32_e32 v18, 16, v65
	v_mul_f32_e32 v16, 0xbfb8aa3b, v12
	v_mul_f32_e32 v17, 0xbfb8aa3b, v13
	v_exp_f32_e32 v16, v16
	v_exp_f32_e32 v17, v17
	v_and_b32_e32 v19, 0xffff0000, v65
	v_pk_mul_f32 v[10:11], v[10:11], v[18:19]
	v_add_f32_e32 v16, 1.0, v16
	v_add_f32_e32 v17, 1.0, v17
	v_rcp_f32_e32 v16, v16
	v_rcp_f32_e32 v17, v17
	v_mul_f32_e32 v31, 0xbfb8aa3b, v27
	v_exp_f32_e32 v30, v30
	v_exp_f32_e32 v31, v31
	v_pk_mul_f32 v[12:13], v[12:13], v[16:17]
	v_lshlrev_b32_e32 v16, 16, v69
	v_and_b32_e32 v17, 0xffff0000, v69
	v_pk_fma_f32 v[2:3], v[2:3], v[16:17], v[10:11]
	v_lshlrev_b32_e32 v10, 16, v77
	v_and_b32_e32 v11, 0xffff0000, v77
	v_pk_fma_f32 v[2:3], v[6:7], v[10:11], v[2:3]
	v_lshlrev_b32_e32 v10, 16, v64
	v_mul_f32_e32 v6, 0xbfb8aa3b, v2
	v_mul_f32_e32 v7, 0xbfb8aa3b, v3
	v_exp_f32_e32 v6, v6
	v_exp_f32_e32 v7, v7
	v_and_b32_e32 v11, 0xffff0000, v64
	v_pk_mul_f32 v[8:9], v[8:9], v[10:11]
	v_add_f32_e32 v6, 1.0, v6
	v_add_f32_e32 v7, 1.0, v7
	v_rcp_f32_e32 v6, v6
	v_rcp_f32_e32 v7, v7
	v_mul_f32_e32 v41, 0xbfb8aa3b, v37
	v_mov_b32_e32 v23, v73
	v_exp_f32_e32 v40, v40
	v_pk_mul_f32 v[2:3], v[2:3], v[6:7]
	v_lshlrev_b32_e32 v6, 16, v68
	v_and_b32_e32 v7, 0xffff0000, v68
	v_pk_fma_f32 v[0:1], v[0:1], v[6:7], v[8:9]
	v_lshlrev_b32_e32 v6, 16, v76
	v_and_b32_e32 v7, 0xffff0000, v76
	v_pk_fma_f32 v[0:1], v[4:5], v[6:7], v[0:1]
	v_exp_f32_e32 v41, v41
	v_mul_f32_e32 v4, 0xbfb8aa3b, v0
	v_mul_f32_e32 v5, 0xbfb8aa3b, v1
	v_exp_f32_e32 v4, v4
	v_exp_f32_e32 v5, v5
	v_add_f32_e32 v28, 1.0, v28
	v_add_f32_e32 v29, 1.0, v29
	v_add_f32_e32 v4, 1.0, v4
	v_add_f32_e32 v5, 1.0, v5
	v_rcp_f32_e32 v4, v4
	v_rcp_f32_e32 v5, v5
	v_mov_b32_e32 v21, v72
	v_mul_f32_e32 v43, 0xbfb8aa3b, v39
	v_rcp_f32_e32 v28, v28
	v_pk_mul_f32 v[0:1], v[0:1], v[4:5]
	v_rcp_f32_e32 v29, v29
	v_mov_b32_e32 v22, v1
	v_mov_b32_e32 v20, v0
	v_pk_mul_f32 v[22:23], v[22:23], v[22:23]
	v_mov_b32_e32 v16, v2
	v_mov_b32_e32 v17, v86
	v_pk_fma_f32 v[20:21], v[20:21], v[20:21], v[22:23]
	v_exp_f32_e32 v42, v42
	v_exp_f32_e32 v43, v43
	v_add_f32_e32 v30, 1.0, v30
	v_add_f32_e32 v31, 1.0, v31
	v_mov_b32_e32 v18, v3
	v_mov_b32_e32 v19, v87
	v_pk_fma_f32 v[16:17], v[16:17], v[16:17], v[20:21]
	v_rcp_f32_e32 v30, v30
	v_rcp_f32_e32 v31, v31
	v_mov_b32_e32 v8, v12
	v_mov_b32_e32 v9, v74
	v_pk_fma_f32 v[16:17], v[18:19], v[18:19], v[16:17]
	v_add_f32_e32 v40, 1.0, v40
	v_add_f32_e32 v41, 1.0, v41
	v_mov_b32_e32 v10, v13
	v_mov_b32_e32 v11, v75
	v_pk_fma_f32 v[8:9], v[8:9], v[8:9], v[16:17]
	v_rcp_f32_e32 v40, v40
	v_rcp_f32_e32 v41, v41
	v_pk_mul_f32 v[24:25], v[24:25], v[28:29]
	v_mov_b32_e32 v4, v14
	v_mov_b32_e32 v5, v104
	v_pk_fma_f32 v[8:9], v[10:11], v[10:11], v[8:9]
	v_add_f32_e32 v42, 1.0, v42
	v_add_f32_e32 v43, 1.0, v43
	v_pk_mul_f32 v[28:29], v[24:25], v[24:25]
	v_mov_b32_e32 v6, v15
	v_mov_b32_e32 v7, v105
	v_pk_fma_f32 v[4:5], v[4:5], v[4:5], v[8:9]
	v_rcp_f32_e32 v42, v42
	v_rcp_f32_e32 v43, v43
	v_pk_mul_f32 v[26:27], v[26:27], v[30:31]
	v_pk_fma_f32 v[4:5], v[6:7], v[6:7], v[4:5]
	v_mov_b32_e32 v6, v28
	v_mov_b32_e32 v7, v108
	v_pk_mul_f32 v[30:31], v[26:27], v[26:27]
	v_pk_add_f32 v[4:5], v[6:7], v[4:5]
	v_mov_b32_e32 v108, v29
	v_pk_mul_f32 v[36:37], v[36:37], v[40:41]
	v_pk_add_f32 v[4:5], v[108:109], v[4:5]
	v_mov_b32_e32 v6, v30
	v_mov_b32_e32 v7, v106
	v_pk_mul_f32 v[40:41], v[36:37], v[36:37]
	v_pk_add_f32 v[4:5], v[6:7], v[4:5]
	v_mov_b32_e32 v106, v31
	v_pk_mul_f32 v[38:39], v[38:39], v[42:43]
	v_pk_add_f32 v[4:5], v[106:107], v[4:5]
	v_mov_b32_e32 v6, v40
	v_mov_b32_e32 v7, v98
	v_pk_mul_f32 v[42:43], v[38:39], v[38:39]
	v_pk_add_f32 v[4:5], v[6:7], v[4:5]
	v_mov_b32_e32 v98, v41
	v_pk_add_f32 v[4:5], v[98:99], v[4:5]
	v_mov_b32_e32 v6, v42
	v_mov_b32_e32 v7, v56
	v_pk_add_f32 v[4:5], v[6:7], v[4:5]
	v_mov_b32_e32 v56, v43
	v_pk_add_f32 v[4:5], v[56:57], v[4:5]
	ds_bpermute_b32 v7, v127, v5
	ds_bpermute_b32 v6, v127, v4
	s_waitcnt lgkmcnt(0)
	v_pk_add_f32 v[4:5], v[4:5], v[6:7]
	ds_bpermute_b32 v7, v126, v5
	ds_bpermute_b32 v6, v126, v4
	s_waitcnt lgkmcnt(0)
	v_pk_add_f32 v[4:5], v[4:5], v[6:7]
	ds_bpermute_b32 v7, v125, v5
	ds_bpermute_b32 v6, v125, v4
	s_waitcnt lgkmcnt(0)
	v_pk_add_f32 v[4:5], v[4:5], v[6:7]
	s_nop 0
	v_pk_add_f32 v[16:17], v[4:5], s[0:1] op_sel_hi:[1,0]
	s_movk_i32 s0, 0x70
	v_mul_f32_e32 v4, 0x4b800000, v17
	v_cmp_gt_f32_e64 s[38:39], s25, v17
	v_cmp_gt_f32_e32 vcc, s25, v16
	s_nop 0
	v_cndmask_b32_e64 v4, v17, v4, s[38:39]
	v_mul_f32_e32 v17, 0x4b800000, v16
	v_cndmask_b32_e32 v16, v16, v17, vcc
	v_rsq_f32_e32 v16, v16
	v_rsq_f32_e32 v4, v4
	v_mul_f32_e32 v17, 0x45800000, v16
	v_mul_f32_e32 v5, 0x45800000, v4
	v_cndmask_b32_e32 v16, v16, v17, vcc
	v_cndmask_b32_e64 v4, v4, v5, s[38:39]
	v_pk_mul_f32 v[0:1], v[0:1], v[16:17] op_sel_hi:[1,0]
	v_pk_mul_f32 v[2:3], v[2:3], v[16:17] op_sel_hi:[1,0]
	v_mul_f32_e32 v18, 0x3db504f3, v4
	v_cvt_pk_bf16_f32 v0, v0, v1
	v_cvt_pk_bf16_f32 v1, v2, v3
	v_pk_mul_f32 v[2:3], v[12:13], v[16:17] op_sel_hi:[1,0]
	v_pk_mul_f32 v[12:13], v[14:15], v[16:17] op_sel_hi:[1,0]
	v_pk_mul_f32 v[4:5], v[72:73], v[18:19] op_sel_hi:[1,0]
	v_pk_mul_f32 v[6:7], v[86:87], v[18:19] op_sel_hi:[1,0]
	v_cvt_pk_bf16_f32 v2, v2, v3
	v_cvt_pk_bf16_f32 v3, v12, v13
	v_pk_mul_f32 v[12:13], v[24:25], v[16:17] op_sel_hi:[1,0]
	v_pk_mul_f32 v[14:15], v[26:27], v[16:17] op_sel_hi:[1,0]
	v_cvt_pk_bf16_f32 v4, v4, v5
	v_cvt_pk_bf16_f32 v5, v6, v7
	v_pk_mul_f32 v[6:7], v[74:75], v[18:19] op_sel_hi:[1,0]
	v_pk_mul_f32 v[8:9], v[104:105], v[18:19] op_sel_hi:[1,0]
	v_cvt_pk_bf16_f32 v12, v12, v13
	v_cvt_pk_bf16_f32 v13, v14, v15
	v_pk_mul_f32 v[14:15], v[36:37], v[16:17] op_sel_hi:[1,0]
	v_pk_mul_f32 v[16:17], v[38:39], v[16:17] op_sel_hi:[1,0]
	v_cvt_pk_bf16_f32 v6, v6, v7
	v_cvt_pk_bf16_f32 v7, v8, v9
	v_pk_mul_f32 v[8:9], v[96:97], v[18:19] op_sel_hi:[1,0]
	v_pk_mul_f32 v[10:11], v[58:59], v[18:19] op_sel_hi:[1,0]
	v_cvt_pk_bf16_f32 v14, v14, v15
	v_cvt_pk_bf16_f32 v15, v16, v17
	v_mul_lo_u32 v16, v187, s96
	v_lshlrev_b32_e32 v17, 5, v128
	v_cvt_pk_bf16_f32 v8, v8, v9
	v_cvt_pk_bf16_f32 v9, v10, v11
	v_pk_mul_f32 v[10:11], v[54:55], v[18:19] op_sel_hi:[1,0]
	v_pk_mul_f32 v[18:19], v[52:53], v[18:19] op_sel_hi:[1,0]
	v_add3_u32 v16, 0, v16, v17
	v_cvt_pk_bf16_f32 v10, v10, v11
	v_cvt_pk_bf16_f32 v11, v18, v19
	ds_write_b128 v16, v[4:7] offset:17408
	ds_write_b128 v16, v[8:11] offset:17424
	ds_write_b128 v16, v[0:3]
	ds_write_b128 v16, v[12:15] offset:16
	v_lshrrev_b32_e32 v4, 6, v186
	v_xor_b32_e32 v4, v4, v216
	v_lshlrev_b32_e32 v5, 1, v187
	v_lshlrev_b32_e32 v4, 4, v4
	v_and_b32_e32 v5, 14, v5
	v_and_or_b32 v4, v4, s0, v5
	v_mul_u32_u24_e32 v5, 0x900, v128
	v_add3_u32 v4, 0, v4, v5
	ds_write_b16 v4, v0 offset:34816
	ds_write_b16_d16_hi v4, v0 offset:34960
	v_cvt_pk_bf16_f32 v0, v212, v213
	ds_write_b16 v4, v0 offset:53248
	ds_write_b16_d16_hi v4, v0 offset:53392
	ds_write_b16 v4, v1 offset:35104
	ds_write_b16_d16_hi v4, v1 offset:35248
	v_cvt_pk_bf16_f32 v0, v174, v175
	ds_write_b16 v4, v0 offset:53536
	ds_write_b16_d16_hi v4, v0 offset:53680
	ds_write_b16 v4, v2 offset:35392
	ds_write_b16_d16_hi v4, v2 offset:35536
	v_cvt_pk_bf16_f32 v0, v178, v179
	ds_write_b16 v4, v0 offset:53824
	ds_write_b16_d16_hi v4, v0 offset:53968
	ds_write_b16 v4, v3 offset:35680
	ds_write_b16_d16_hi v4, v3 offset:35824
	v_cvt_pk_bf16_f32 v0, v176, v177
	ds_write_b16 v4, v0 offset:54112
	ds_write_b16_d16_hi v4, v0 offset:54256
	ds_write_b16 v4, v12 offset:35968
	ds_write_b16_d16_hi v4, v12 offset:36112
	v_cvt_pk_bf16_f32 v0, v60, v61
	ds_write_b16 v4, v0 offset:54400
	ds_write_b16_d16_hi v4, v0 offset:54544
	ds_write_b16 v4, v13 offset:36256
	ds_write_b16_d16_hi v4, v13 offset:36400
	v_cvt_pk_bf16_f32 v0, v62, v63
	ds_write_b16 v4, v0 offset:54688
	ds_write_b16_d16_hi v4, v0 offset:54832
	ds_write_b16 v4, v14 offset:36544
	ds_write_b16_d16_hi v4, v14 offset:36688
	v_cvt_pk_bf16_f32 v0, v48, v49
	ds_write_b16 v4, v0 offset:54976
	ds_write_b16_d16_hi v4, v0 offset:55120
	ds_write_b16 v4, v15 offset:36832
	ds_write_b16_d16_hi v4, v15 offset:36976
	v_cvt_pk_bf16_f32 v0, v50, v51
	v_cmp_gt_u32_e64 s[38:39], 64, v186
	ds_write_b16 v4, v0 offset:55264
	ds_write_b16_d16_hi v4, v0 offset:55408
	s_and_saveexec_b64 s[4:5], s[38:39]
	s_cbranch_execz .LBB0_194
	v_lshl_or_b32 v2, s1, 6, v186
	v_readlane_b32 s0, v251, 47
	v_readlane_b32 s1, v251, 48
	s_ashr_i32 s3, s2, 31
	s_mov_b32 s8, 0xc2ce8ed0
	v_mov_b64_e32 v[0:1], s[0:1]
	s_movk_i32 s0, 0xc0
	v_mad_i64_i32 v[0:1], s[0:1], v2, s0, v[0:1]
	v_readlane_b32 s0, v255, 8
	s_mul_i32 s0, s0, 24
	v_readlane_b32 s1, v255, 9
	s_add_i32 s0, s2, s0
	s_ashr_i32 s1, s0, 31
	s_lshl_b64 s[6:7], s[0:1], 2
	v_lshl_add_u64 v[0:1], s[2:3], 2, v[0:1]
	s_add_u32 s2, s70, s6
	s_addc_u32 s3, s71, s7
	global_load_dword v2, v[0:1], off
	global_load_dword v3, v129, s[2:3]
	s_add_i32 s0, s0, 12
	s_ashr_i32 s1, s0, 31
	s_lshl_b64 s[2:3], s[0:1], 2
	s_add_u32 s0, s70, s2
	s_addc_u32 s1, s71, s3
	global_load_dword v4, v129, s[0:1]
	s_add_u32 s0, s68, s6
	s_addc_u32 s1, s69, s7
	s_mov_b32 s7, 0x3fb8aa3b
	s_mov_b32 s9, 0x42b17218
	s_mov_b32 s6, 0xbfb8aa3b
	s_mov_b32 s10, 0xb2a5705f
	s_mov_b32 s11, 0x42ce8ed0
	s_mov_b32 s16, 0xc2b17218
	s_mov_b32 s17, 0x3f2aaaab
	s_mov_b32 s26, 0x3f317218
	s_mov_b32 s27, 0x33800000
	v_cmp_gt_u32_e64 s[42:43], 60, v214
	s_waitcnt vmcnt(1)
	v_add_f32_e32 v3, v2, v3
	global_load_dword v2, v[0:1], off offset:48
	s_waitcnt vmcnt(0)
	v_add_f32_e32 v6, v2, v4
	global_load_dword v2, v129, s[0:1]
	s_add_u32 s0, s68, s2
	s_addc_u32 s1, s69, s3
	v_readlane_b32 s2, v254, 41
	s_waitcnt vmcnt(0)
	v_mul_f32_e32 v4, 0x3fb8aa3b, v2
	v_fma_f32 v5, v2, s7, -v4
	v_rndne_f32_e32 v7, v4
	v_fmac_f32_e32 v5, 0x32a5705f, v2
	v_sub_f32_e32 v4, v4, v7
	v_add_f32_e32 v4, v4, v5
	v_exp_f32_e32 v4, v4
	v_cvt_i32_f32_e32 v5, v7
	v_cmp_ngt_f32_e32 vcc, s8, v2
	v_max_f32_e32 v7, 0, v3
	v_ldexp_f32 v4, v4, v5
	v_cndmask_b32_e32 v4, 0, v4, vcc
	v_cmp_nlt_f32_e32 vcc, s9, v2
	s_nop 1
	v_cndmask_b32_e32 v2, v249, v4, vcc
	v_mul_f32_e64 v4, |v3|, s6
	v_fma_f32 v5, |v3|, s6, -v4
	v_rndne_f32_e32 v8, v4
	v_fma_f32 v5, |v3|, s10, v5
	v_sub_f32_e32 v4, v4, v8
	v_add_f32_e32 v4, v4, v5
	v_exp_f32_e32 v4, v4
	v_cvt_i32_f32_e32 v5, v8
	v_cmp_ngt_f32_e64 vcc, |v3|, s11
	v_ldexp_f32 v4, v4, v5
	s_nop 0
	v_cndmask_b32_e32 v4, 0, v4, vcc
	v_cmp_nlt_f32_e64 vcc, |v3|, s16
	s_nop 1
	v_cndmask_b32_e32 v3, v249, v4, vcc
	v_add_f32_e32 v8, 1.0, v3
	v_add_f32_e32 v4, -1.0, v8
	v_sub_f32_e32 v5, v4, v8
	v_add_f32_e32 v5, 1.0, v5
	v_sub_f32_e32 v4, v3, v4
	v_add_f32_e32 v9, v4, v5
	v_frexp_mant_f32_e32 v4, v8
	v_cmp_gt_f32_e32 vcc, s17, v4
	v_cvt_f64_f32_e32 v[4:5], v8
	v_frexp_exp_i32_f64_e32 v4, v[4:5]
	v_subbrev_co_u32_e32 v4, vcc, 0, v4, vcc
	v_sub_u32_e32 v5, 0, v4
	v_ldexp_f32 v8, v8, v5
	v_ldexp_f32 v5, v9, v5
	v_add_f32_e32 v9, -1.0, v8
	v_add_f32_e32 v10, 1.0, v9
	v_sub_f32_e32 v10, v8, v10
	v_add_f32_e32 v10, v5, v10
	v_add_f32_e32 v11, v9, v10
	v_sub_f32_e32 v9, v9, v11
	v_add_f32_e32 v9, v10, v9
	v_add_f32_e32 v10, 1.0, v8
	v_add_f32_e32 v12, -1.0, v10
	v_sub_f32_e32 v8, v8, v12
	v_add_f32_e32 v5, v5, v8
	v_add_f32_e32 v8, v10, v5
	v_sub_f32_e32 v10, v10, v8
	v_add_f32_e32 v5, v5, v10
	v_rcp_f32_e32 v10, v8
	v_cvt_f32_i32_e32 v4, v4
	v_cmp_neq_f32_e32 vcc, s33, v3
	v_mul_f32_e32 v12, v11, v10
	v_mul_f32_e32 v13, v8, v12
	v_fma_f32 v14, v12, v8, -v13
	v_fmac_f32_e32 v14, v12, v5
	v_add_f32_e32 v15, v13, v14
	v_sub_f32_e32 v16, v11, v15
	v_sub_f32_e32 v11, v11, v16
	v_sub_f32_e32 v13, v15, v13
	v_sub_f32_e32 v11, v11, v15
	v_add_f32_e32 v9, v9, v11
	v_sub_f32_e32 v11, v13, v14
	v_add_f32_e32 v9, v11, v9
	v_add_f32_e32 v11, v16, v9
	v_mul_f32_e32 v13, v10, v11
	v_mul_f32_e32 v14, v8, v13
	v_fma_f32 v8, v13, v8, -v14
	v_fmac_f32_e32 v8, v13, v5
	v_sub_f32_e32 v5, v16, v11
	v_add_f32_e32 v5, v9, v5
	v_add_f32_e32 v9, v14, v8
	v_sub_f32_e32 v15, v11, v9
	v_sub_f32_e32 v11, v11, v15
	v_sub_f32_e32 v14, v9, v14
	v_sub_f32_e32 v9, v11, v9
	v_add_f32_e32 v5, v5, v9
	v_sub_f32_e32 v8, v14, v8
	v_add_f32_e32 v5, v8, v5
	v_add_f32_e32 v8, v12, v13
	v_add_f32_e32 v5, v15, v5
	v_sub_f32_e32 v9, v8, v12
	v_mul_f32_e32 v5, v10, v5
	v_sub_f32_e32 v9, v13, v9
	v_add_f32_e32 v5, v9, v5
	v_mul_f32_e32 v12, 0x3f317218, v4
	v_add_f32_e32 v9, v8, v5
	v_fma_f32 v13, v4, s26, -v12
	v_mul_f32_e32 v10, v9, v9
	v_fmac_f32_e32 v13, 0xb102e308, v4
	v_sub_f32_e32 v4, v9, v8
	v_fmamk_f32 v11, v10, 0x3e9b6dac, v238
	v_sub_f32_e32 v4, v5, v4
	v_add_f32_e32 v5, v12, v13
	v_fmaak_f32 v11, v10, v11, 0x3f2aaada
	v_sub_f32_e32 v8, v5, v12
	v_ldexp_f32 v12, v9, 1
	v_mul_f32_e32 v9, v9, v10
	v_mul_f32_e32 v9, v9, v11
	v_add_f32_e32 v10, v12, v9
	v_sub_f32_e32 v11, v10, v12
	v_ldexp_f32 v4, v4, 1
	v_sub_f32_e32 v9, v9, v11
	v_add_f32_e32 v4, v4, v9
	v_add_f32_e32 v9, v10, v4
	v_sub_f32_e32 v10, v9, v10
	v_sub_f32_e32 v4, v4, v10
	v_add_f32_e32 v10, v5, v9
	v_sub_f32_e32 v11, v10, v5
	v_sub_f32_e32 v12, v10, v11
	v_sub_f32_e32 v8, v13, v8
	v_sub_f32_e32 v5, v5, v12
	v_sub_f32_e32 v9, v9, v11
	v_add_f32_e32 v5, v9, v5
	v_add_f32_e32 v9, v8, v4
	v_sub_f32_e32 v11, v9, v8
	v_sub_f32_e32 v12, v9, v11
	v_sub_f32_e32 v8, v8, v12
	v_sub_f32_e32 v4, v4, v11
	v_add_f32_e32 v5, v9, v5
	v_add_f32_e32 v4, v4, v8
	v_add_f32_e32 v8, v10, v5
	v_sub_f32_e32 v9, v8, v10
	v_sub_f32_e32 v5, v5, v9
	v_add_f32_e32 v4, v4, v5
	global_load_dword v5, v129, s[0:1]
	v_add_f32_e32 v4, v8, v4
	v_cndmask_b32_e32 v4, v249, v4, vcc
	v_cmp_lt_f32_e64 vcc, |v3|, s27
	s_nop 1
	v_cndmask_b32_e32 v3, v4, v3, vcc
	v_add_f32_e32 v3, v7, v3
	v_mul_f32_e64 v4, v3, -v2
	s_waitcnt vmcnt(0)
	v_mul_f32_e32 v7, 0x3fb8aa3b, v5
	v_fma_f32 v8, v5, s7, -v7
	v_rndne_f32_e32 v9, v7
	v_fmac_f32_e32 v8, 0x32a5705f, v5
	v_sub_f32_e32 v7, v7, v9
	v_add_f32_e32 v7, v7, v8
	v_exp_f32_e32 v7, v7
	v_cvt_i32_f32_e32 v8, v9
	v_cmp_ngt_f32_e32 vcc, s8, v5
	v_ldexp_f32 v7, v7, v8
	s_nop 0
	v_cndmask_b32_e32 v7, 0, v7, vcc
	v_cmp_nlt_f32_e32 vcc, s9, v5
	v_max_f32_e32 v8, 0, v6
	s_nop 0
	v_cndmask_b32_e32 v5, v249, v7, vcc
	v_mul_f32_e64 v7, |v6|, s6
	v_fma_f32 v9, |v6|, s6, -v7
	v_rndne_f32_e32 v10, v7
	v_fma_f32 v9, |v6|, s10, v9
	v_sub_f32_e32 v7, v7, v10
	v_add_f32_e32 v7, v7, v9
	v_exp_f32_e32 v7, v7
	v_cvt_i32_f32_e32 v9, v10
	v_cmp_ngt_f32_e64 vcc, |v6|, s11
	v_ldexp_f32 v7, v7, v9
	s_nop 0
	v_cndmask_b32_e32 v7, 0, v7, vcc
	v_cmp_nlt_f32_e64 vcc, |v6|, s16
	s_nop 1
	v_cndmask_b32_e32 v9, v249, v7, vcc
	v_add_f32_e32 v10, 1.0, v9
	v_add_f32_e32 v6, -1.0, v10
	v_sub_f32_e32 v7, v6, v10
	v_add_f32_e32 v7, 1.0, v7
	v_sub_f32_e32 v6, v9, v6
	v_add_f32_e32 v11, v6, v7
	v_frexp_mant_f32_e32 v6, v10
	v_cmp_gt_f32_e32 vcc, s17, v6
	v_cvt_f64_f32_e32 v[6:7], v10
	v_frexp_exp_i32_f64_e32 v6, v[6:7]
	v_subbrev_co_u32_e32 v6, vcc, 0, v6, vcc
	v_sub_u32_e32 v7, 0, v6
	v_ldexp_f32 v10, v10, v7
	v_ldexp_f32 v7, v11, v7
	v_add_f32_e32 v11, -1.0, v10
	v_add_f32_e32 v12, 1.0, v11
	v_sub_f32_e32 v12, v10, v12
	v_add_f32_e32 v12, v7, v12
	v_add_f32_e32 v13, v11, v12
	v_sub_f32_e32 v11, v11, v13
	v_add_f32_e32 v11, v12, v11
	v_add_f32_e32 v12, 1.0, v10
	v_add_f32_e32 v14, -1.0, v12
	v_sub_f32_e32 v10, v10, v14
	v_add_f32_e32 v7, v7, v10
	v_add_f32_e32 v10, v12, v7
	v_sub_f32_e32 v12, v12, v10
	v_add_f32_e32 v7, v7, v12
	v_rcp_f32_e32 v12, v10
	v_cvt_f32_i32_e32 v6, v6
	v_cmp_neq_f32_e32 vcc, s33, v9
	v_mul_f32_e32 v14, v13, v12
	v_mul_f32_e32 v15, v10, v14
	v_fma_f32 v16, v14, v10, -v15
	v_fmac_f32_e32 v16, v14, v7
	v_add_f32_e32 v17, v15, v16
	v_sub_f32_e32 v18, v13, v17
	v_sub_f32_e32 v13, v13, v18
	v_sub_f32_e32 v15, v17, v15
	v_sub_f32_e32 v13, v13, v17
	v_add_f32_e32 v11, v11, v13
	v_sub_f32_e32 v13, v15, v16
	v_add_f32_e32 v11, v13, v11
	v_add_f32_e32 v13, v18, v11
	v_mul_f32_e32 v15, v12, v13
	v_mul_f32_e32 v16, v10, v15
	v_fma_f32 v10, v15, v10, -v16
	v_fmac_f32_e32 v10, v15, v7
	v_sub_f32_e32 v7, v18, v13
	v_add_f32_e32 v7, v11, v7
	v_add_f32_e32 v11, v16, v10
	v_sub_f32_e32 v17, v13, v11
	v_sub_f32_e32 v13, v13, v17
	v_sub_f32_e32 v16, v11, v16
	v_sub_f32_e32 v11, v13, v11
	v_add_f32_e32 v7, v7, v11
	v_sub_f32_e32 v10, v16, v10
	v_add_f32_e32 v7, v10, v7
	v_add_f32_e32 v10, v14, v15
	v_add_f32_e32 v7, v17, v7
	v_sub_f32_e32 v11, v10, v14
	v_mul_f32_e32 v7, v12, v7
	v_sub_f32_e32 v11, v15, v11
	v_add_f32_e32 v7, v11, v7
	v_mul_f32_e32 v14, 0x3f317218, v6
	v_add_f32_e32 v11, v10, v7
	v_fma_f32 v15, v6, s26, -v14
	v_mul_f32_e32 v12, v11, v11
	v_fmac_f32_e32 v15, 0xb102e308, v6
	v_sub_f32_e32 v6, v11, v10
	v_fmamk_f32 v13, v12, 0x3e9b6dac, v238
	v_sub_f32_e32 v6, v7, v6
	v_add_f32_e32 v7, v14, v15
	v_fmaak_f32 v13, v12, v13, 0x3f2aaada
	v_sub_f32_e32 v10, v7, v14
	v_ldexp_f32 v14, v11, 1
	v_mul_f32_e32 v11, v11, v12
	v_mul_f32_e32 v11, v11, v13
	v_add_f32_e32 v12, v14, v11
	v_sub_f32_e32 v13, v12, v14
	v_ldexp_f32 v6, v6, 1
	v_sub_f32_e32 v11, v11, v13
	v_add_f32_e32 v6, v6, v11
	v_add_f32_e32 v11, v12, v6
	v_sub_f32_e32 v12, v11, v12
	v_sub_f32_e32 v6, v6, v12
	v_add_f32_e32 v12, v7, v11
	v_sub_f32_e32 v13, v12, v7
	v_sub_f32_e32 v14, v12, v13
	v_sub_f32_e32 v10, v15, v10
	v_sub_f32_e32 v7, v7, v14
	v_sub_f32_e32 v11, v11, v13
	v_add_f32_e32 v7, v11, v7
	v_add_f32_e32 v11, v10, v6
	v_sub_f32_e32 v13, v11, v10
	v_sub_f32_e32 v14, v11, v13
	v_sub_f32_e32 v10, v10, v14
	v_sub_f32_e32 v6, v6, v13
	v_add_f32_e32 v7, v11, v7
	v_add_f32_e32 v6, v6, v10
	v_add_f32_e32 v10, v12, v7
	v_sub_f32_e32 v11, v10, v12
	v_sub_f32_e32 v7, v7, v11
	v_add_f32_e32 v6, v6, v7
	v_add_f32_e32 v6, v10, v6
	v_cndmask_b32_e32 v6, v249, v6, vcc
	v_cmp_lt_f32_e64 vcc, |v9|, s27
	s_nop 1
	v_cndmask_b32_e32 v6, v6, v9, vcc
	v_add_f32_e32 v6, v8, v6
	global_load_dword v8, v[0:1], off offset:96
	v_mul_f32_e64 v7, v6, -v5
	global_load_dword v0, v[0:1], off offset:144
	s_waitcnt vmcnt(1)
	v_mul_f32_e32 v9, 0xbfb8aa3b, v8
	v_fma_f32 v10, v8, s6, -v9
	v_rndne_f32_e32 v11, v9
	v_fmac_f32_e32 v10, 0xb2a5705f, v8
	v_sub_f32_e32 v9, v9, v11
	v_add_f32_e32 v9, v9, v10
	v_exp_f32_e32 v9, v9
	v_cvt_i32_f32_e32 v10, v11
	v_cmp_nlt_f32_e32 vcc, s11, v8
	s_waitcnt vmcnt(0)
	v_mul_f32_e32 v1, 0xbfb8aa3b, v0
	v_ldexp_f32 v9, v9, v10
	v_cndmask_b32_e32 v9, 0, v9, vcc
	v_cmp_ngt_f32_e32 vcc, s16, v8
	v_rndne_f32_e32 v10, v1
	s_nop 0
	v_cndmask_b32_e32 v8, v249, v9, vcc
	v_fma_f32 v9, v0, s6, -v1
	v_fmac_f32_e32 v9, 0xb2a5705f, v0
	v_sub_f32_e32 v1, v1, v10
	v_add_f32_e32 v1, v1, v9
	v_exp_f32_e32 v1, v1
	v_cvt_i32_f32_e32 v9, v10
	v_cmp_nlt_f32_e32 vcc, s11, v0
	v_add_f32_e32 v8, 1.0, v8
	s_mov_b32 s6, 0x3fb8aa3b
	v_ldexp_f32 v1, v1, v9
	v_cndmask_b32_e32 v1, 0, v1, vcc
	v_cmp_ngt_f32_e32 vcc, s16, v0
	v_add_u32_e32 v9, 4, v124
	s_nop 0
	v_cndmask_b32_e32 v0, v249, v1, vcc
	v_cmp_ne_u32_e32 vcc, 0, v214
	v_add_f32_e32 v0, 1.0, v0
	s_nop 0
	v_subbrev_co_u32_e64 v1, s[40:41], 0, v214, vcc
	v_cmp_eq_u32_e64 s[40:41], 63, v214
	v_lshlrev_b32_e32 v1, 2, v1
	ds_bpermute_b32 v1, v1, v4
	v_cndmask_b32_e64 v9, v9, v242, s[40:41]
	ds_bpermute_b32 v9, v9, v7
	s_waitcnt lgkmcnt(1)
	v_fma_f32 v1, v3, -v2, v1
	v_cndmask_b32_e32 v1, v4, v1, vcc
	s_waitcnt lgkmcnt(0)
	v_fma_f32 v2, v6, -v5, v9
	v_cndmask_b32_e64 v2, v2, v7, s[40:41]
	v_cmp_gt_u32_e64 s[40:41], 2, v214
	v_cmp_gt_u32_e32 vcc, 62, v214
	v_add_u32_e32 v4, 8, v124
	v_cndmask_b32_e64 v3, -2, 0, s[40:41]
	v_add_lshl_u32 v3, v3, v214, 2
	ds_bpermute_b32 v3, v3, v1
	v_cndmask_b32_e32 v4, v124, v4, vcc
	ds_bpermute_b32 v4, v4, v2
	s_waitcnt lgkmcnt(1)
	v_add_f32_e32 v3, v1, v3
	v_cndmask_b32_e64 v1, v3, v1, s[40:41]
	s_waitcnt lgkmcnt(0)
	v_add_f32_e32 v3, v2, v4
	v_cndmask_b32_e32 v2, v2, v3, vcc
	v_cmp_gt_u32_e32 vcc, 4, v214
	v_add_u32_e32 v4, 16, v124
	v_cndmask_b32_e64 v4, v124, v4, s[42:43]
	v_cndmask_b32_e64 v3, -4, 0, vcc
	v_add_lshl_u32 v3, v3, v214, 2
	ds_bpermute_b32 v3, v3, v1
	ds_bpermute_b32 v4, v4, v2
	s_waitcnt lgkmcnt(1)
	v_add_f32_e32 v3, v1, v3
	v_cndmask_b32_e32 v1, v3, v1, vcc
	s_waitcnt lgkmcnt(0)
	v_add_f32_e32 v3, v2, v4
	v_cmp_gt_u32_e32 vcc, 8, v214
	v_cndmask_b32_e64 v2, v2, v3, s[42:43]
	v_cmp_gt_u32_e64 s[42:43], 56, v214
	v_cndmask_b32_e64 v3, -8, 0, vcc
	v_add_lshl_u32 v3, v3, v214, 2
	v_add_u32_e32 v4, 32, v124
	ds_bpermute_b32 v3, v3, v1
	v_cndmask_b32_e64 v4, v124, v4, s[42:43]
	ds_bpermute_b32 v4, v4, v2
	s_waitcnt lgkmcnt(1)
	v_add_f32_e32 v3, v1, v3
	v_cndmask_b32_e32 v1, v3, v1, vcc
	s_waitcnt lgkmcnt(0)
	v_add_f32_e32 v3, v2, v4
	v_cmp_gt_u32_e32 vcc, 16, v214
	v_cndmask_b32_e64 v2, v2, v3, s[42:43]
	v_cmp_gt_u32_e64 s[42:43], 48, v214
	v_cndmask_b32_e64 v3, -16, 0, vcc
	v_add_lshl_u32 v3, v3, v214, 2
	v_add_u32_e32 v4, 64, v124
	ds_bpermute_b32 v3, v3, v1
	v_cndmask_b32_e64 v4, v124, v4, s[42:43]
	ds_bpermute_b32 v4, v4, v2
	s_waitcnt lgkmcnt(1)
	v_add_f32_e32 v3, v1, v3
	v_cndmask_b32_e32 v1, v3, v1, vcc
	s_waitcnt lgkmcnt(0)
	v_add_f32_e32 v3, v2, v4
	v_cndmask_b32_e64 v2, v2, v3, s[42:43]
	v_lshlrev_b32_e32 v3, 2, v216
	v_cmp_gt_u32_e32 vcc, 32, v214
	v_and_b32_e32 v3, 0x7c, v3
	v_add_u32_e32 v4, 0x80, v124
	ds_bpermute_b32 v3, v3, v1
	v_cndmask_b32_e32 v4, v124, v4, vcc
	ds_bpermute_b32 v4, v4, v2
	s_waitcnt lgkmcnt(1)
	v_add_f32_e32 v3, v1, v3
	v_cndmask_b32_e32 v1, v3, v1, vcc
	s_waitcnt lgkmcnt(0)
	v_add_f32_e32 v3, v2, v4
	v_cndmask_b32_e32 v2, v2, v3, vcc
	v_div_scale_f32 v3, s[0:1], v8, v8, 1.0
	v_rcp_f32_e32 v4, v3
	s_nop 0
	v_fma_f32 v5, -v3, v4, 1.0
	v_fmac_f32_e32 v4, v5, v4
	v_div_scale_f32 v5, vcc, 1.0, v8, 1.0
	v_mul_f32_e32 v6, v5, v4
	v_fma_f32 v7, -v3, v6, v5
	v_fmac_f32_e32 v6, v7, v4
	v_fma_f32 v3, -v3, v6, v5
	v_div_fmas_f32 v3, v3, v4, v6
	v_div_scale_f32 v4, s[0:1], v0, v0, 1.0
	v_rcp_f32_e32 v5, v4
	v_div_fixup_f32 v3, v3, v8, 1.0
	v_readlane_b32 s0, v1, 63
	v_readlane_b32 s1, v2, 0
	v_fma_f32 v6, -v4, v5, 1.0
	v_fmac_f32_e32 v5, v6, v5
	v_div_scale_f32 v6, vcc, 1.0, v0, 1.0
	v_mul_f32_e32 v7, v6, v5
	v_fma_f32 v8, -v4, v7, v6
	v_fmac_f32_e32 v7, v8, v5
	v_fma_f32 v4, -v4, v7, v6
	v_div_fmas_f32 v4, v4, v5, v7
	v_div_fixup_f32 v0, v4, v0, 1.0
	v_mul_f32_e32 v4, 0x3fb8aa3b, v1
	v_fma_f32 v5, v1, s7, -v4
	v_rndne_f32_e32 v6, v4
	v_fmac_f32_e32 v5, 0x32a5705f, v1
	v_sub_f32_e32 v4, v4, v6
	v_add_f32_e32 v4, v4, v5
	v_exp_f32_e32 v4, v4
	v_cvt_i32_f32_e32 v5, v6
	v_cmp_ngt_f32_e32 vcc, s8, v1
	v_ldexp_f32 v4, v4, v5
	v_mul_f32_e32 v5, 0x3fb8aa3b, v2
	v_fma_f32 v6, v2, s7, -v5
	v_rndne_f32_e32 v7, v5
	v_fmac_f32_e32 v6, 0x32a5705f, v2
	v_sub_f32_e32 v5, v5, v7
	v_add_f32_e32 v5, v5, v6
	v_exp_f32_e32 v5, v5
	v_cvt_i32_f32_e32 v6, v7
	v_cndmask_b32_e32 v4, 0, v4, vcc
	v_cmp_nlt_f32_e32 vcc, s9, v1
	v_ldexp_f32 v5, v5, v6
	v_lshl_add_u32 v6, v214, 2, s2
	ds_write_b32 v6, v1
	v_sub_f32_e32 v1, s0, v1
	v_mul_f32_e32 v7, 0x3fb8aa3b, v1
	v_fma_f32 v8, v1, s7, -v7
	v_rndne_f32_e32 v9, v7
	v_fmac_f32_e32 v8, 0x32a5705f, v1
	v_sub_f32_e32 v7, v7, v9
	v_add_f32_e32 v7, v7, v8
	v_exp_f32_e32 v7, v7
	v_cvt_i32_f32_e32 v8, v9
	v_cndmask_b32_e32 v4, v249, v4, vcc
	v_cmp_ngt_f32_e32 vcc, s8, v2
	v_lshl_add_u32 v6, v186, 2, s2
	v_ldexp_f32 v7, v7, v8
	v_cndmask_b32_e32 v5, 0, v5, vcc
	v_cmp_nlt_f32_e32 vcc, s9, v2
	ds_write2st64_b32 v6, v2, v3 offset0:1 offset1:2
	ds_write2st64_b32 v6, v0, v4 offset0:3 offset1:4
	v_cndmask_b32_e32 v5, v249, v5, vcc
	v_cmp_ngt_f32_e32 vcc, s8, v1
	v_mul_f32_e32 v0, v0, v5
	ds_write_b32 v6, v0 offset:2304
	v_cndmask_b32_e32 v7, 0, v7, vcc
	v_cmp_nlt_f32_e32 vcc, s9, v1
	s_nop 1
	v_cndmask_b32_e32 v1, v249, v7, vcc
	ds_write2st64_b32 v6, v5, v1 offset0:5 offset1:6
	v_sub_f32_e32 v1, s1, v2
	v_mul_f32_e32 v2, 0x3fb8aa3b, v1
	v_fma_f32 v7, v1, s7, -v2
	v_rndne_f32_e32 v8, v2
	v_fmac_f32_e32 v7, 0x32a5705f, v1
	v_sub_f32_e32 v2, v2, v8
	v_add_f32_e32 v2, v2, v7
	v_exp_f32_e32 v2, v2
	v_cvt_i32_f32_e32 v7, v8
	v_cmp_ngt_f32_e32 vcc, s8, v1
	s_mov_b32 s7, 0xc2ce8ed0
	s_mov_b32 s8, 0x42b17218
	v_ldexp_f32 v2, v2, v7
	v_cndmask_b32_e32 v2, 0, v2, vcc
	v_cmp_nlt_f32_e32 vcc, s9, v1
	s_nop 1
	v_cndmask_b32_e32 v1, v249, v2, vcc
	v_mul_f32_e32 v2, v3, v4
	ds_write2st64_b32 v6, v1, v2 offset0:7 offset1:8
	s_and_b64 exec, exec, s[40:41]
	s_cbranch_execz .LBB0_194
	v_mov_b32_e32 v0, s1
	v_mov_b32_e32 v1, s0
	v_cmp_eq_u32_e32 vcc, 0, v214
	s_ashr_i32 s29, s28, 31
	s_lshl_b64 s[0:1], s[28:29], 3
	v_cndmask_b32_e32 v0, v0, v1, vcc
	v_mul_f32_e32 v1, 0x3fb8aa3b, v0
	v_fma_f32 v2, v0, s6, -v1
	v_rndne_f32_e32 v3, v1
	v_fmac_f32_e32 v2, 0x32a5705f, v0
	v_sub_f32_e32 v1, v1, v3
	v_add_f32_e32 v1, v1, v2
	v_exp_f32_e32 v1, v1
	v_cvt_i32_f32_e32 v2, v3
	v_cmp_ngt_f32_e32 vcc, s7, v0
	v_readlane_b32 s2, v251, 29
	s_add_u32 s0, s2, s0
	v_ldexp_f32 v1, v1, v2
	v_cndmask_b32_e32 v1, 0, v1, vcc
	v_cmp_nlt_f32_e32 vcc, s8, v0
	v_readlane_b32 s2, v251, 30
	s_addc_u32 s1, s2, s1
	v_cndmask_b32_e32 v0, v249, v1, vcc
	global_store_dword v124, v0, s[0:1]

	.amdhsa_kernel _Z6mk_fwd4Args
		.amdhsa_group_segment_fixed_size 0
		.amdhsa_private_segment_fixed_size 0
		.amdhsa_kernarg_size 400
		.amdhsa_user_sgpr_count 2
		.amdhsa_user_sgpr_dispatch_ptr 0
		.amdhsa_user_sgpr_queue_ptr 0
		.amdhsa_user_sgpr_kernarg_segment_ptr 1
		.amdhsa_user_sgpr_dispatch_id 0
		.amdhsa_user_sgpr_kernarg_preload_length 0
		.amdhsa_user_sgpr_kernarg_preload_offset 0
		.amdhsa_user_sgpr_private_segment_size 0
		.amdhsa_uses_dynamic_stack 0
		.amdhsa_enable_private_segment 0
		.amdhsa_system_sgpr_workgroup_id_x 1
		.amdhsa_system_sgpr_workgroup_id_y 0
		.amdhsa_system_sgpr_workgroup_id_z 0
		.amdhsa_system_sgpr_workgroup_info 0
		.amdhsa_system_vgpr_workitem_id 2
		.amdhsa_next_free_vgpr 256
		.amdhsa_next_free_sgpr 100
		.amdhsa_accum_offset 256
		.amdhsa_reserve_vcc 1
		.amdhsa_float_round_mode_32 0
		.amdhsa_float_round_mode_16_64 0
		.amdhsa_float_denorm_mode_32 3
		.amdhsa_float_denorm_mode_16_64 3
		.amdhsa_dx10_clamp 1
		.amdhsa_ieee_mode 1
		.amdhsa_fp16_overflow 0
		.amdhsa_tg_split 0
		.amdhsa_exception_fp_ieee_invalid_op 0
		.amdhsa_exception_fp_denorm_src 0
		.amdhsa_exception_fp_ieee_div_zero 0
		.amdhsa_exception_fp_ieee_overflow 0
		.amdhsa_exception_fp_ieee_underflow 0
		.amdhsa_exception_fp_ieee_inexact 0
		.amdhsa_exception_int_div_zero 0
	.end_amdhsa_kernel

amdhsa.kernels:
  - .agpr_count:     0
    .args:
      - .offset:         0
        .size:           144
        .value_kind:     by_value
      - .offset:         144
        .size:           4
        .value_kind:     hidden_block_count_x
      - .offset:         148
        .size:           4
        .value_kind:     hidden_block_count_y
      - .offset:         152
        .size:           4
        .value_kind:     hidden_block_count_z
      - .offset:         156
        .size:           2
        .value_kind:     hidden_group_size_x
      - .offset:         158
        .size:           2
        .value_kind:     hidden_group_size_y
      - .offset:         160
        .size:           2
        .value_kind:     hidden_group_size_z
      - .offset:         162
        .size:           2
        .value_kind:     hidden_remainder_x
      - .offset:         164
        .size:           2
        .value_kind:     hidden_remainder_y
      - .offset:         166
        .size:           2
        .value_kind:     hidden_remainder_z
      - .offset:         184
        .size:           8
        .value_kind:     hidden_global_offset_x
      - .offset:         192
        .size:           8
        .value_kind:     hidden_global_offset_y
      - .offset:         200
        .size:           8
        .value_kind:     hidden_global_offset_z
      - .offset:         208
        .size:           2
        .value_kind:     hidden_grid_dims
      - .offset:         232
        .size:           8
        .value_kind:     hidden_multigrid_sync_arg
      - .offset:         264
        .size:           4
        .value_kind:     hidden_dynamic_lds_size
    .group_segment_fixed_size: 0
    .kernarg_segment_align: 8
    .kernarg_segment_size: 400
    .language:       OpenCL C
    .language_version:
      - 2
      - 0
    .max_flat_workgroup_size: 512
    .name:           _Z6mk_fwd4Args
    .private_segment_fixed_size: 0
    .sgpr_count:     106
    .sgpr_spill_count: 291
    .symbol:         _Z6mk_fwd4Args.kd
    .uniform_work_group_size: 1
    .uses_dynamic_stack: false
    .vgpr_count:     256
    .vgpr_spill_count: 0
    .wavefront_size: 64
